# gate epilogue: the 71 load-independent v_cvt_f32_i32 moved above the parameter-load s_waitcnt vmcnt(0) (more work under the loads), on top of the row-by-row store schedule
# speedup vs baseline: 1.0106x; 1.0008x over previous
;     __device__ __forceinline__ void operator()(const f32x4 (&acc)[2][2][4][2], const Unit& u, int wr, int wc, int fr, int fq) const {
;     ...
;         const int row0 = u.pm * BM + wr * 64 + fr, col0 = u.pn * BM + wc * 64 + 16 * fq;
;         const int gn = u.pn >> 2, gbase = (gn < 3) ? 3072 + 1024 * gn : 0;
;         f32x4 bv[2][2];
; #pragma unroll
;         for (int bj = 0; bj < 2; ++bj)
; #pragma unroll
;             for (int n = 0; n < 2; ++n) bv[bj][n] = *(const f32x4*)(bias + col0 + 8 * bj + 4 * n) * -1.44269504f;
;         f32x4 wv[2][2];
; #pragma unroll
;         for (int bj = 0; bj < 2; ++bj)
; #pragma unroll
;             for (int n = 0; n < 2; ++n) wv[bj][n] = *(const f32x4*)(SW + col0 + 8 * bj + 4 * n) * -1.44269504f;
;         float rsv[8];
; #pragma unroll
;         for (int i = 0; i < 8; ++i) rsv[i] = SH[row0 + (i >> 2) * HALF + (i & 3) * 16];
.LBB0_1195:
	s_lshl_b32 s0, s59, 8
	v_mov_b32_e32 v130, v179
	v_mov_b32_e32 v154, v1
	s_or_b32 s0, s0, s53
	v_cvt_f32_i32_e32 v212, v122
	v_lshl_add_u32 v144, v130, 4, s0
	s_lshl_b32 s0, s38, 8
	v_ashrrev_i32_e32 v145, 31, v144
	s_add_i32 s0, s0, s50
	v_lshlrev_b64 v[142:143], 2, v[144:145]
	v_add_u32_e32 v164, s0, v154
	v_lshl_add_u64 v[160:161], s[10:11], 0, v[142:143]
	v_ashrrev_i32_e32 v165, 31, v164
	global_load_dwordx4 v[130:133], v[160:161], off
	global_load_dwordx4 v[134:137], v[160:161], off offset:16
	global_load_dwordx4 v[138:141], v[160:161], off offset:32
	s_nop 0
	global_load_dwordx4 v[160:163], v[160:161], off offset:48
	v_lshl_add_u64 v[142:143], s[14:15], 0, v[142:143]
	v_lshl_add_u64 v[170:171], v[164:165], 2, s[16:17]
	global_load_dwordx4 v[166:169], v[142:143], off
	global_load_dwordx4 v[194:197], v[142:143], off offset:16
	global_load_dwordx4 v[198:201], v[142:143], off offset:32
	global_load_dwordx4 v[202:205], v[142:143], off offset:48
	global_load_dword v206, v[170:171], off
	global_load_dword v188, v[170:171], off offset:64
	global_load_dword v186, v[170:171], off offset:128
	global_load_dword v184, v[170:171], off offset:192
	global_load_dword v182, v[170:171], off offset:512
	global_load_dword v180, v[170:171], off offset:576
	global_load_dword v178, v[170:171], off offset:640
	global_load_dword v122, v[170:171], off offset:704
	s_ashr_i32 s0, s59, 2
	s_lshl_b32 s1, s0, 10
	v_mov_b64_e32 v[142:143], s[12:13]
	s_add_i32 s2, s1, 0xc00
	v_cvt_f32_i32_e32 v209, v127
	v_cvt_f32_i32_e32 v208, v126
	v_cvt_f32_i32_e32 v215, v125
	v_cvt_f32_i32_e32 v214, v124
	s_cmp_lt_i32 s0, 3
	v_mad_i64_i32 v[124:125], s[0:1], v164, s57, v[142:143]
	s_cselect_b32 s0, s2, 0
	v_cvt_f32_i32_e32 v211, v129
	v_cvt_f32_i32_e32 v210, v128
	s_ashr_i32 s1, s0, 31
	v_cvt_f32_i32_e32 v115, v115
	v_cvt_f32_i32_e32 v114, v114
	v_cvt_f32_i32_e32 v99, v99
	v_cvt_f32_i32_e32 v98, v98
	v_cvt_f32_i32_e32 v83, v83
	v_cvt_f32_i32_e32 v82, v82
	v_cvt_f32_i32_e32 v67, v67
	v_cvt_f32_i32_e32 v66, v66
	v_cvt_f32_i32_e32 v51, v51
	v_cvt_f32_i32_e32 v50, v50
	v_cvt_f32_i32_e32 v35, v35
	v_cvt_f32_i32_e32 v34, v34
	v_cvt_f32_i32_e32 v19, v19
	v_cvt_f32_i32_e32 v18, v18
	v_and_b32_e32 v154, 0x3f0, v144
	v_lshl_add_u64 v[124:125], v[124:125], 0, s[0:1]
	v_cvt_f32_i32_e32 v117, v117
	v_cvt_f32_i32_e32 v116, v116
	v_cvt_f32_i32_e32 v111, v111
	v_cvt_f32_i32_e32 v110, v110
	v_cvt_f32_i32_e32 v101, v101
	v_cvt_f32_i32_e32 v100, v100
	v_cvt_f32_i32_e32 v95, v95
	v_cvt_f32_i32_e32 v94, v94
	v_cvt_f32_i32_e32 v85, v85
	v_cvt_f32_i32_e32 v84, v84
	v_cvt_f32_i32_e32 v79, v79
	v_cvt_f32_i32_e32 v78, v78
	v_cvt_f32_i32_e32 v69, v69
	v_cvt_f32_i32_e32 v68, v68
	v_cvt_f32_i32_e32 v63, v63
	v_cvt_f32_i32_e32 v62, v62
	v_cvt_f32_i32_e32 v53, v53
	v_cvt_f32_i32_e32 v52, v52
	v_cvt_f32_i32_e32 v47, v47
	v_cvt_f32_i32_e32 v46, v46
	v_cvt_f32_i32_e32 v37, v37
	v_cvt_f32_i32_e32 v36, v36
	v_cvt_f32_i32_e32 v31, v31
	v_cvt_f32_i32_e32 v30, v30
	v_cvt_f32_i32_e32 v21, v21
	v_cvt_f32_i32_e32 v20, v20
	v_cvt_f32_i32_e32 v15, v15
	v_cvt_f32_i32_e32 v14, v14
	v_add_u32_e32 v207, 32, v164
	v_lshl_add_u64 v[216:217], v[124:125], 0, v[154:155]
	v_add_u32_e32 v189, 0xa0, v164
	v_cvt_f32_i32_e32 v213, v123
	v_add_u32_e32 v123, 0xb0, v164
	v_cvt_f32_i32_e32 v119, v119
	v_cvt_f32_i32_e32 v118, v118
	v_cvt_f32_i32_e32 v109, v109
	v_cvt_f32_i32_e32 v108, v108
	v_cvt_f32_i32_e32 v103, v103
	v_cvt_f32_i32_e32 v102, v102
	v_cvt_f32_i32_e32 v93, v93
	v_cvt_f32_i32_e32 v121, v121
	v_cvt_f32_i32_e32 v120, v120
	v_cvt_f32_i32_e32 v113, v113
	v_cvt_f32_i32_e32 v112, v112
	v_cvt_f32_i32_e32 v107, v107
	v_cvt_f32_i32_e32 v106, v106
	v_cvt_f32_i32_e32 v105, v105
	v_cvt_f32_i32_e32 v104, v104
	v_cvt_f32_i32_e32 v92, v92
	v_cvt_f32_i32_e32 v87, v87
	v_cvt_f32_i32_e32 v86, v86
	v_cvt_f32_i32_e32 v97, v97
	v_cvt_f32_i32_e32 v96, v96
	v_cvt_f32_i32_e32 v91, v91
	v_cvt_f32_i32_e32 v90, v90
	v_cvt_f32_i32_e32 v89, v89
	v_cvt_f32_i32_e32 v88, v88
	v_cvt_f32_i32_e32 v77, v77
	v_cvt_f32_i32_e32 v76, v76
	v_cvt_f32_i32_e32 v71, v71
	v_cvt_f32_i32_e32 v70, v70
	v_cvt_f32_i32_e32 v81, v81
	v_cvt_f32_i32_e32 v80, v80
	v_cvt_f32_i32_e32 v75, v75
	v_cvt_f32_i32_e32 v74, v74
	v_cvt_f32_i32_e32 v73, v73
	v_cvt_f32_i32_e32 v72, v72
	v_cvt_f32_i32_e32 v61, v61
	v_cvt_f32_i32_e32 v60, v60
	v_cvt_f32_i32_e32 v55, v55
	v_cvt_f32_i32_e32 v54, v54
	v_cvt_f32_i32_e32 v65, v65
	v_cvt_f32_i32_e32 v64, v64
	v_cvt_f32_i32_e32 v59, v59
	v_cvt_f32_i32_e32 v58, v58
	v_cvt_f32_i32_e32 v57, v57
	v_cvt_f32_i32_e32 v56, v56
	v_cvt_f32_i32_e32 v45, v45
	v_cvt_f32_i32_e32 v44, v44
	v_cvt_f32_i32_e32 v39, v39
	v_cvt_f32_i32_e32 v38, v38
	v_cvt_f32_i32_e32 v49, v49
	v_cvt_f32_i32_e32 v48, v48
	v_cvt_f32_i32_e32 v43, v43
	v_cvt_f32_i32_e32 v42, v42
	v_cvt_f32_i32_e32 v41, v41
	v_cvt_f32_i32_e32 v40, v40
	v_cvt_f32_i32_e32 v29, v29
	v_cvt_f32_i32_e32 v28, v28
	v_cvt_f32_i32_e32 v23, v23
	v_cvt_f32_i32_e32 v22, v22
	v_cvt_f32_i32_e32 v33, v33
	v_cvt_f32_i32_e32 v32, v32
	v_cvt_f32_i32_e32 v27, v27
	v_cvt_f32_i32_e32 v26, v26
	v_cvt_f32_i32_e32 v25, v25
	v_cvt_f32_i32_e32 v24, v24
	v_cvt_f32_i32_e32 v7, v7
	v_cvt_f32_i32_e32 v6, v6
	v_cvt_f32_i32_e32 v3, v3
	v_cvt_f32_i32_e32 v2, v2
	v_cvt_f32_i32_e32 v17, v17
	v_cvt_f32_i32_e32 v16, v16
	v_cvt_f32_i32_e32 v11, v11
	v_cvt_f32_i32_e32 v13, v13
	v_cvt_f32_i32_e32 v12, v12
	v_cvt_f32_i32_e32 v10, v10
	v_cvt_f32_i32_e32 v9, v9
	v_cvt_f32_i32_e32 v8, v8
	v_cvt_f32_i32_e32 v5, v5
	v_cvt_f32_i32_e32 v4, v4
	s_waitcnt vmcnt(0)
;     __device__ __forceinline__ void operator()(const f32x4 (&acc)[2][2][4][2], const Unit& u, int wr, int wc, int fr, int fq) const {
;     ...
; #pragma unroll
;         for (int ai = 0; ai < 2; ++ai)
; #pragma unroll
;             for (int m = 0; m < 4; ++m) { unsigned char* rowp = O + (size_t)(row0 + ai * HALF + m * 16) * 8704 + gbase + (col0 & 1023);
;                 const float rs = rsv[ai * 4 + m];
;                 u32x4 w; EPG_Q4(w.x, acc[ai][0][m][0], wv[0][0], rs, bv[0][0]); EPG_Q4(w.y, acc[ai][0][m][1], wv[0][1], rs, bv[0][1]);
;                 EPG_Q4(w.z, acc[ai][1][m][0], wv[1][0], rs, bv[1][0]); EPG_Q4(w.w, acc[ai][1][m][1], wv[1][1], rs, bv[1][1]);
;                 *(u32x4*)rowp = w; }
	v_pk_mul_f32 v[172:173], v[130:131], s[22:23] op_sel_hi:[1,0]
	v_pk_mul_f32 v[170:171], v[132:133], s[22:23] op_sel_hi:[1,0]
	v_pk_mul_f32 v[174:175], v[166:167], s[22:23] op_sel_hi:[1,0]
	v_pk_mul_f32 v[124:125], v[162:163], s[22:23] op_sel_hi:[1,0]
	v_pk_mul_f32 v[162:163], v[174:175], v[208:209]
	v_pk_mul_f32 v[176:177], v[168:169], s[22:23] op_sel_hi:[1,0]
	v_pk_mul_f32 v[130:131], v[202:203], s[22:23] op_sel_hi:[1,0]
	v_pk_fma_f32 v[162:163], v[162:163], v[206:207], v[172:173] op_sel_hi:[1,0,1]
	v_pk_mul_f32 v[128:129], v[160:161], s[22:23] op_sel_hi:[1,0]
	v_pk_mul_f32 v[132:133], v[204:205], s[22:23] op_sel_hi:[1,0]
	v_pk_mul_f32 v[160:161], v[176:177], v[210:211]
	v_exp_f32_e32 v162, v162
	v_exp_f32_e32 v163, v163
	v_pk_mul_f32 v[114:115], v[130:131], v[114:115]
	v_pk_fma_f32 v[160:161], v[160:161], v[206:207], v[170:171] op_sel_hi:[1,0,1]
	v_pk_mul_f32 v[116:117], v[132:133], v[116:117]
	v_pk_fma_f32 v[114:115], v[114:115], v[206:207], v[128:129] op_sel_hi:[1,0,1]
	v_exp_f32_e32 v160, v160
	v_exp_f32_e32 v161, v161
	v_pk_fma_f32 v[116:117], v[116:117], v[206:207], v[124:125] op_sel_hi:[1,0,1]
	v_exp_f32_e32 v114, v114
	v_exp_f32_e32 v115, v115
	v_exp_f32_e32 v116, v116
	v_exp_f32_e32 v117, v117
	v_pk_mul_f32 v[166:167], v[194:195], s[22:23] op_sel_hi:[1,0]
	v_pk_add_f32 v[162:163], v[162:163], 1.0 op_sel_hi:[1,0]
	v_add_u32_e32 v193, 16, v164
	v_add_u32_e32 v192, 48, v164
	v_add_u32_e32 v191, 0x80, v164
	v_add_u32_e32 v190, 0x90, v164
	v_pk_mul_f32 v[144:145], v[136:137], s[22:23] op_sel_hi:[1,0]
	v_pk_mul_f32 v[164:165], v[134:135], s[22:23] op_sel_hi:[1,0]
	v_pk_mul_f32 v[136:137], v[138:139], s[22:23] op_sel_hi:[1,0]
	v_pk_mul_f32 v[168:169], v[196:197], s[22:23] op_sel_hi:[1,0]
	v_pk_mul_f32 v[138:139], v[198:199], s[22:23] op_sel_hi:[1,0]
	v_pk_mul_f32 v[196:197], v[166:167], v[212:213]
	v_rcp_f32_e32 v162, v162
	v_rcp_f32_e32 v163, v163
	v_pk_mul_f32 v[134:135], v[140:141], s[22:23] op_sel_hi:[1,0]
	v_pk_mul_f32 v[140:141], v[200:201], s[22:23] op_sel_hi:[1,0]
	v_pk_mul_f32 v[194:195], v[168:169], v[214:215]
	v_pk_fma_f32 v[196:197], v[196:197], v[206:207], v[164:165] op_sel_hi:[1,0,1]
	v_pk_add_f32 v[160:161], v[160:161], 1.0 op_sel_hi:[1,0]
	v_pk_mul_f32 v[118:119], v[138:139], v[118:119]
	v_pk_add_f32 v[114:115], v[114:115], 1.0 op_sel_hi:[1,0]
	v_pk_fma_f32 v[194:195], v[194:195], v[206:207], v[144:145] op_sel_hi:[1,0,1]
	v_exp_f32_e32 v196, v196
	v_rcp_f32_e32 v160, v160
	v_rcp_f32_e32 v161, v161
	v_exp_f32_e32 v197, v197
	v_pk_mul_f32 v[120:121], v[140:141], v[120:121]
	v_pk_fma_f32 v[118:119], v[118:119], v[206:207], v[136:137] op_sel_hi:[1,0,1]
	v_pk_add_f32 v[116:117], v[116:117], 1.0 op_sel_hi:[1,0]
	v_rcp_f32_e32 v114, v114
	v_rcp_f32_e32 v115, v115
	v_mov_b64_e32 v[126:127], s[24:25]
	v_exp_f32_e32 v194, v194
	v_exp_f32_e32 v195, v195
	v_pk_fma_f32 v[120:121], v[120:121], v[206:207], v[134:135] op_sel_hi:[1,0,1]
	v_exp_f32_e32 v118, v118
	v_exp_f32_e32 v119, v119
	v_rcp_f32_e32 v116, v116
	v_rcp_f32_e32 v117, v117
	v_pk_fma_f32 v[162:163], v[162:163], s[26:27], v[126:127] op_sel_hi:[1,0,0]
	v_exp_f32_e32 v120, v120
	v_exp_f32_e32 v121, v121
	v_max_f32_e32 v163, 0x4b000001, v163
	v_max_f32_e32 v162, 0x4b000001, v162
	v_pk_fma_f32 v[160:161], v[160:161], s[26:27], v[126:127] op_sel_hi:[1,0,0]
	v_perm_b32 v198, v163, v162, s58
	v_pk_add_f32 v[162:163], v[196:197], 1.0 op_sel_hi:[1,0]
	v_pk_fma_f32 v[114:115], v[114:115], s[26:27], v[126:127] op_sel_hi:[1,0,0]
	v_max_f32_e32 v199, 0x4b000001, v161
	v_max_f32_e32 v200, 0x4b000001, v160
	v_pk_add_f32 v[160:161], v[194:195], 1.0 op_sel_hi:[1,0]
	v_rcp_f32_e32 v162, v162
	v_rcp_f32_e32 v163, v163
	v_pk_add_f32 v[118:119], v[118:119], 1.0 op_sel_hi:[1,0]
	v_pk_fma_f32 v[116:117], v[116:117], s[26:27], v[126:127] op_sel_hi:[1,0,0]
	v_max_f32_e32 v115, 0x4b000001, v115
	v_max_f32_e32 v114, 0x4b000001, v114
	v_rcp_f32_e32 v194, v160
	v_rcp_f32_e32 v195, v161
	v_pk_add_f32 v[120:121], v[120:121], 1.0 op_sel_hi:[1,0]
	v_rcp_f32_e32 v118, v118
	v_rcp_f32_e32 v119, v119
	v_perm_b32 v114, v115, v114, s58
	v_max_f32_e32 v115, 0x4b000001, v117
	v_max_f32_e32 v116, 0x4b000001, v116
	v_rcp_f32_e32 v120, v120
	v_rcp_f32_e32 v121, v121
	v_perm_b32 v115, v115, v116, s58
	v_pk_fma_f32 v[162:163], v[162:163], s[26:27], v[126:127] op_sel_hi:[1,0,0]
	v_pk_fma_f32 v[194:195], v[194:195], s[26:27], v[126:127] op_sel_hi:[1,0,0]
	v_max_f32_e32 v161, 0x4b000001, v163
	v_max_f32_e32 v162, 0x4b000001, v162
	v_pk_fma_f32 v[118:119], v[118:119], s[26:27], v[126:127] op_sel_hi:[1,0,0]
	v_perm_b32 v161, v161, v162, s58
	v_max_f32_e32 v162, 0x4b000001, v195
	v_max_f32_e32 v163, 0x4b000001, v194
	v_pk_fma_f32 v[120:121], v[120:121], s[26:27], v[126:127] op_sel_hi:[1,0,0]
	v_max_f32_e32 v119, 0x4b000001, v119
	v_max_f32_e32 v118, 0x4b000001, v118
	v_perm_b32 v162, v162, v163, s58
	v_perm_b32 v118, v119, v118, s58
	v_max_f32_e32 v119, 0x4b000001, v121
	v_max_f32_e32 v120, 0x4b000001, v120
	v_lshl_or_b32 v163, v115, 16, v114
	v_perm_b32 v160, v199, v200, s58
	v_perm_b32 v119, v119, v120, s58
	v_lshl_or_b32 v160, v160, 16, v198
	v_lshl_or_b32 v161, v162, 16, v161
	v_lshl_or_b32 v162, v119, 16, v118
	global_store_dwordx4 v[216:217], v[160:163], off
	v_pk_mul_f32 v[98:99], v[130:131], v[98:99]
	v_pk_mul_f32 v[110:111], v[174:175], v[110:111]
	v_pk_mul_f32 v[100:101], v[132:133], v[100:101]
	v_pk_fma_f32 v[98:99], v[98:99], v[188:189], v[128:129] op_sel_hi:[1,0,1]
	v_pk_fma_f32 v[110:111], v[110:111], v[188:189], v[172:173] op_sel_hi:[1,0,1]
	v_pk_fma_f32 v[100:101], v[100:101], v[188:189], v[124:125] op_sel_hi:[1,0,1]
	v_exp_f32_e32 v98, v98
	v_exp_f32_e32 v99, v99
	v_exp_f32_e32 v110, v110
;     __device__ __forceinline__ void operator()(const f32x4 (&acc)[2][2][4][2], const Unit& u, int wr, int wc, int fr, int fq) const {
;     ...
; #pragma unroll
;         for (int ai = 0; ai < 2; ++ai)
; #pragma unroll
;             for (int m = 0; m < 4; ++m) { unsigned char* rowp = O + (size_t)(row0 + ai * HALF + m * 16) * 8704 + gbase + (col0 & 1023);
;                 const float rs = rsv[ai * 4 + m];
;                 u32x4 w; EPG_Q4(w.x, acc[ai][0][m][0], wv[0][0], rs, bv[0][0]); EPG_Q4(w.y, acc[ai][0][m][1], wv[0][1], rs, bv[0][1]);
;                 EPG_Q4(w.z, acc[ai][1][m][0], wv[1][0], rs, bv[1][0]); EPG_Q4(w.w, acc[ai][1][m][1], wv[1][1], rs, bv[1][1]);
;                 *(u32x4*)rowp = w; }
	v_exp_f32_e32 v111, v111
	v_exp_f32_e32 v100, v100
	v_exp_f32_e32 v101, v101
	v_pk_mul_f32 v[108:109], v[168:169], v[108:109]
	v_pk_mul_f32 v[102:103], v[138:139], v[102:103]
	v_pk_add_f32 v[98:99], v[98:99], 1.0 op_sel_hi:[1,0]
	v_pk_mul_f32 v[112:113], v[176:177], v[112:113]
	v_pk_add_f32 v[110:111], v[110:111], 1.0 op_sel_hi:[1,0]
	v_pk_mul_f32 v[106:107], v[166:167], v[106:107]
	v_pk_fma_f32 v[108:109], v[108:109], v[188:189], v[144:145] op_sel_hi:[1,0,1]
	v_pk_mul_f32 v[104:105], v[140:141], v[104:105]
	v_pk_fma_f32 v[102:103], v[102:103], v[188:189], v[136:137] op_sel_hi:[1,0,1]
	v_pk_add_f32 v[100:101], v[100:101], 1.0 op_sel_hi:[1,0]
	v_rcp_f32_e32 v98, v98
	v_rcp_f32_e32 v99, v99
	v_pk_fma_f32 v[112:113], v[112:113], v[188:189], v[170:171] op_sel_hi:[1,0,1]
	v_rcp_f32_e32 v110, v110
	v_rcp_f32_e32 v111, v111
	v_pk_fma_f32 v[106:107], v[106:107], v[188:189], v[164:165] op_sel_hi:[1,0,1]
	v_exp_f32_e32 v108, v108
	v_exp_f32_e32 v109, v109
	v_pk_fma_f32 v[104:105], v[104:105], v[188:189], v[134:135] op_sel_hi:[1,0,1]
	v_exp_f32_e32 v102, v102
	v_exp_f32_e32 v103, v103
	v_rcp_f32_e32 v100, v100
	v_rcp_f32_e32 v101, v101
	v_exp_f32_e32 v112, v112
	v_exp_f32_e32 v113, v113
	v_exp_f32_e32 v106, v106
	v_exp_f32_e32 v107, v107
	v_exp_f32_e32 v104, v104
	v_exp_f32_e32 v105, v105
	v_pk_fma_f32 v[98:99], v[98:99], s[26:27], v[126:127] op_sel_hi:[1,0,0]
	v_pk_fma_f32 v[110:111], v[110:111], s[26:27], v[126:127] op_sel_hi:[1,0,0]
	v_pk_add_f32 v[108:109], v[108:109], 1.0 op_sel_hi:[1,0]
	v_pk_add_f32 v[102:103], v[102:103], 1.0 op_sel_hi:[1,0]
	v_pk_fma_f32 v[100:101], v[100:101], s[26:27], v[126:127] op_sel_hi:[1,0,0]
	v_max_f32_e32 v99, 0x4b000001, v99
	v_max_f32_e32 v98, 0x4b000001, v98
	v_pk_add_f32 v[112:113], v[112:113], 1.0 op_sel_hi:[1,0]
	v_max_f32_e32 v111, 0x4b000001, v111
	v_max_f32_e32 v110, 0x4b000001, v110
	v_pk_add_f32 v[106:107], v[106:107], 1.0 op_sel_hi:[1,0]
	v_rcp_f32_e32 v108, v108
	v_rcp_f32_e32 v109, v109
	v_pk_add_f32 v[104:105], v[104:105], 1.0 op_sel_hi:[1,0]
	v_rcp_f32_e32 v102, v102
	v_rcp_f32_e32 v103, v103
	v_perm_b32 v98, v99, v98, s58
	v_max_f32_e32 v99, 0x4b000001, v101
	v_max_f32_e32 v100, 0x4b000001, v100
	v_rcp_f32_e32 v112, v112
	v_rcp_f32_e32 v113, v113
	v_perm_b32 v116, v111, v110, s58
	v_rcp_f32_e32 v110, v106
	v_rcp_f32_e32 v111, v107
	v_rcp_f32_e32 v104, v104
	v_rcp_f32_e32 v105, v105
	v_perm_b32 v99, v99, v100, s58
	v_pk_fma_f32 v[108:109], v[108:109], s[26:27], v[126:127] op_sel_hi:[1,0,0]
	v_pk_fma_f32 v[102:103], v[102:103], s[26:27], v[126:127] op_sel_hi:[1,0,0]
	v_pk_fma_f32 v[112:113], v[112:113], s[26:27], v[126:127] op_sel_hi:[1,0,0]
	v_pk_fma_f32 v[110:111], v[110:111], s[26:27], v[126:127] op_sel_hi:[1,0,0]
	v_max_f32_e32 v109, 0x4b000001, v109
	v_max_f32_e32 v108, 0x4b000001, v108
	v_pk_fma_f32 v[104:105], v[104:105], s[26:27], v[126:127] op_sel_hi:[1,0,0]
	v_max_f32_e32 v103, 0x4b000001, v103
	v_max_f32_e32 v102, 0x4b000001, v102
	v_mad_i64_i32 v[114:115], s[2:3], v193, s57, v[142:143]
	v_max_f32_e32 v113, 0x4b000001, v113
	v_max_f32_e32 v112, 0x4b000001, v112
	v_max_f32_e32 v107, 0x4b000001, v111
	v_max_f32_e32 v110, 0x4b000001, v110
	v_perm_b32 v108, v109, v108, s58
	v_perm_b32 v102, v103, v102, s58
	v_max_f32_e32 v103, 0x4b000001, v105
	v_max_f32_e32 v104, 0x4b000001, v104
	v_lshl_or_b32 v109, v99, 16, v98
	v_lshl_add_u64 v[114:115], v[114:115], 0, s[0:1]
	v_perm_b32 v106, v113, v112, s58
	v_perm_b32 v107, v107, v110, s58
	v_perm_b32 v103, v103, v104, s58
	v_lshl_add_u64 v[114:115], v[114:115], 0, v[154:155]
	v_lshl_or_b32 v106, v106, 16, v116
	v_lshl_or_b32 v107, v108, 16, v107
	v_lshl_or_b32 v108, v103, 16, v102
	global_store_dwordx4 v[114:115], v[106:109], off
	v_pk_mul_f32 v[82:83], v[130:131], v[82:83]
	v_pk_mul_f32 v[94:95], v[174:175], v[94:95]
	v_pk_mul_f32 v[84:85], v[132:133], v[84:85]
	v_pk_fma_f32 v[82:83], v[82:83], v[186:187], v[128:129] op_sel_hi:[1,0,1]
	v_pk_fma_f32 v[94:95], v[94:95], v[186:187], v[172:173] op_sel_hi:[1,0,1]
	v_pk_fma_f32 v[84:85], v[84:85], v[186:187], v[124:125] op_sel_hi:[1,0,1]
	v_exp_f32_e32 v82, v82
	v_exp_f32_e32 v83, v83
	v_exp_f32_e32 v94, v94
	v_exp_f32_e32 v95, v95
	v_exp_f32_e32 v84, v84
	v_exp_f32_e32 v85, v85
	v_pk_mul_f32 v[92:93], v[168:169], v[92:93]
	v_pk_mul_f32 v[86:87], v[138:139], v[86:87]
	v_pk_add_f32 v[82:83], v[82:83], 1.0 op_sel_hi:[1,0]
	v_pk_mul_f32 v[96:97], v[176:177], v[96:97]
	v_pk_add_f32 v[94:95], v[94:95], 1.0 op_sel_hi:[1,0]
	v_pk_mul_f32 v[90:91], v[166:167], v[90:91]
	v_pk_fma_f32 v[92:93], v[92:93], v[186:187], v[144:145] op_sel_hi:[1,0,1]
	v_pk_mul_f32 v[88:89], v[140:141], v[88:89]
	v_pk_fma_f32 v[86:87], v[86:87], v[186:187], v[136:137] op_sel_hi:[1,0,1]
	v_pk_add_f32 v[84:85], v[84:85], 1.0 op_sel_hi:[1,0]
	v_rcp_f32_e32 v82, v82
	v_rcp_f32_e32 v83, v83
	v_pk_fma_f32 v[96:97], v[96:97], v[186:187], v[170:171] op_sel_hi:[1,0,1]
	v_rcp_f32_e32 v94, v94
	v_rcp_f32_e32 v95, v95
	v_pk_fma_f32 v[90:91], v[90:91], v[186:187], v[164:165] op_sel_hi:[1,0,1]
	v_exp_f32_e32 v92, v92
	v_exp_f32_e32 v93, v93
	v_pk_fma_f32 v[88:89], v[88:89], v[186:187], v[134:135] op_sel_hi:[1,0,1]
	v_exp_f32_e32 v86, v86
	v_exp_f32_e32 v87, v87
	v_rcp_f32_e32 v84, v84
	v_rcp_f32_e32 v85, v85
	v_exp_f32_e32 v96, v96
	v_exp_f32_e32 v97, v97
	v_exp_f32_e32 v90, v90
	v_exp_f32_e32 v91, v91
	v_exp_f32_e32 v88, v88
	v_exp_f32_e32 v89, v89
	v_pk_fma_f32 v[82:83], v[82:83], s[26:27], v[126:127] op_sel_hi:[1,0,0]
	v_pk_fma_f32 v[94:95], v[94:95], s[26:27], v[126:127] op_sel_hi:[1,0,0]
	v_pk_add_f32 v[92:93], v[92:93], 1.0 op_sel_hi:[1,0]
	v_pk_add_f32 v[86:87], v[86:87], 1.0 op_sel_hi:[1,0]
	v_pk_fma_f32 v[84:85], v[84:85], s[26:27], v[126:127] op_sel_hi:[1,0,0]
;     __device__ __forceinline__ void operator()(const f32x4 (&acc)[2][2][4][2], const Unit& u, int wr, int wc, int fr, int fq) const {
;     ...
; #pragma unroll
;         for (int ai = 0; ai < 2; ++ai)
; #pragma unroll
;             for (int m = 0; m < 4; ++m) { unsigned char* rowp = O + (size_t)(row0 + ai * HALF + m * 16) * 8704 + gbase + (col0 & 1023);
;                 const float rs = rsv[ai * 4 + m];
;                 u32x4 w; EPG_Q4(w.x, acc[ai][0][m][0], wv[0][0], rs, bv[0][0]); EPG_Q4(w.y, acc[ai][0][m][1], wv[0][1], rs, bv[0][1]);
;                 EPG_Q4(w.z, acc[ai][1][m][0], wv[1][0], rs, bv[1][0]); EPG_Q4(w.w, acc[ai][1][m][1], wv[1][1], rs, bv[1][1]);
;                 *(u32x4*)rowp = w; }
	v_max_f32_e32 v83, 0x4b000001, v83
	v_max_f32_e32 v82, 0x4b000001, v82
	v_pk_add_f32 v[96:97], v[96:97], 1.0 op_sel_hi:[1,0]
	v_max_f32_e32 v95, 0x4b000001, v95
	v_max_f32_e32 v94, 0x4b000001, v94
	v_pk_add_f32 v[90:91], v[90:91], 1.0 op_sel_hi:[1,0]
	v_rcp_f32_e32 v92, v92
	v_rcp_f32_e32 v93, v93
	v_pk_add_f32 v[88:89], v[88:89], 1.0 op_sel_hi:[1,0]
	v_rcp_f32_e32 v86, v86
	v_rcp_f32_e32 v87, v87
	v_perm_b32 v82, v83, v82, s58
	v_max_f32_e32 v83, 0x4b000001, v85
	v_max_f32_e32 v84, 0x4b000001, v84
	v_rcp_f32_e32 v96, v96
	v_rcp_f32_e32 v97, v97
	v_perm_b32 v100, v95, v94, s58
	v_rcp_f32_e32 v94, v90
	v_rcp_f32_e32 v95, v91
	v_rcp_f32_e32 v88, v88
	v_rcp_f32_e32 v89, v89
	v_perm_b32 v83, v83, v84, s58
	v_pk_fma_f32 v[92:93], v[92:93], s[26:27], v[126:127] op_sel_hi:[1,0,0]
	v_pk_fma_f32 v[86:87], v[86:87], s[26:27], v[126:127] op_sel_hi:[1,0,0]
	v_pk_fma_f32 v[96:97], v[96:97], s[26:27], v[126:127] op_sel_hi:[1,0,0]
	v_pk_fma_f32 v[94:95], v[94:95], s[26:27], v[126:127] op_sel_hi:[1,0,0]
	v_max_f32_e32 v93, 0x4b000001, v93
	v_max_f32_e32 v92, 0x4b000001, v92
	v_pk_fma_f32 v[88:89], v[88:89], s[26:27], v[126:127] op_sel_hi:[1,0,0]
	v_max_f32_e32 v87, 0x4b000001, v87
	v_max_f32_e32 v86, 0x4b000001, v86
	v_mad_i64_i32 v[98:99], s[2:3], v207, s57, v[142:143]
	v_max_f32_e32 v97, 0x4b000001, v97
	v_max_f32_e32 v96, 0x4b000001, v96
	v_max_f32_e32 v91, 0x4b000001, v95
	v_max_f32_e32 v94, 0x4b000001, v94
	v_perm_b32 v92, v93, v92, s58
	v_perm_b32 v86, v87, v86, s58
	v_max_f32_e32 v87, 0x4b000001, v89
	v_max_f32_e32 v88, 0x4b000001, v88
	v_lshl_or_b32 v93, v83, 16, v82
	v_lshl_add_u64 v[98:99], v[98:99], 0, s[0:1]
	v_perm_b32 v90, v97, v96, s58
	v_perm_b32 v91, v91, v94, s58
	v_perm_b32 v87, v87, v88, s58
	v_lshl_add_u64 v[98:99], v[98:99], 0, v[154:155]
	v_lshl_or_b32 v90, v90, 16, v100
	v_lshl_or_b32 v91, v92, 16, v91
	v_lshl_or_b32 v92, v87, 16, v86
	global_store_dwordx4 v[98:99], v[90:93], off
	v_pk_mul_f32 v[66:67], v[130:131], v[66:67]
	v_pk_mul_f32 v[78:79], v[174:175], v[78:79]
	v_pk_mul_f32 v[68:69], v[132:133], v[68:69]
	v_pk_fma_f32 v[66:67], v[66:67], v[184:185], v[128:129] op_sel_hi:[1,0,1]
	v_pk_fma_f32 v[78:79], v[78:79], v[184:185], v[172:173] op_sel_hi:[1,0,1]
	v_pk_fma_f32 v[68:69], v[68:69], v[184:185], v[124:125] op_sel_hi:[1,0,1]
	v_exp_f32_e32 v66, v66
	v_exp_f32_e32 v67, v67
	v_exp_f32_e32 v78, v78
	v_exp_f32_e32 v79, v79
	v_exp_f32_e32 v68, v68
	v_exp_f32_e32 v69, v69
	v_pk_mul_f32 v[76:77], v[168:169], v[76:77]
	v_pk_mul_f32 v[70:71], v[138:139], v[70:71]
	v_pk_add_f32 v[66:67], v[66:67], 1.0 op_sel_hi:[1,0]
	v_pk_mul_f32 v[80:81], v[176:177], v[80:81]
	v_pk_add_f32 v[78:79], v[78:79], 1.0 op_sel_hi:[1,0]
	v_pk_mul_f32 v[74:75], v[166:167], v[74:75]
	v_pk_fma_f32 v[76:77], v[76:77], v[184:185], v[144:145] op_sel_hi:[1,0,1]
	v_pk_mul_f32 v[72:73], v[140:141], v[72:73]
	v_pk_fma_f32 v[70:71], v[70:71], v[184:185], v[136:137] op_sel_hi:[1,0,1]
	v_pk_add_f32 v[68:69], v[68:69], 1.0 op_sel_hi:[1,0]
	v_rcp_f32_e32 v66, v66
	v_rcp_f32_e32 v67, v67
	v_pk_fma_f32 v[80:81], v[80:81], v[184:185], v[170:171] op_sel_hi:[1,0,1]
	v_rcp_f32_e32 v78, v78
	v_rcp_f32_e32 v79, v79
	v_pk_fma_f32 v[74:75], v[74:75], v[184:185], v[164:165] op_sel_hi:[1,0,1]
	v_exp_f32_e32 v76, v76
	v_exp_f32_e32 v77, v77
	v_pk_fma_f32 v[72:73], v[72:73], v[184:185], v[134:135] op_sel_hi:[1,0,1]
	v_exp_f32_e32 v70, v70
	v_exp_f32_e32 v71, v71
	v_rcp_f32_e32 v68, v68
	v_rcp_f32_e32 v69, v69
	v_exp_f32_e32 v80, v80
	v_exp_f32_e32 v81, v81
	v_exp_f32_e32 v74, v74
	v_exp_f32_e32 v75, v75
	v_exp_f32_e32 v72, v72
	v_exp_f32_e32 v73, v73
	v_pk_fma_f32 v[66:67], v[66:67], s[26:27], v[126:127] op_sel_hi:[1,0,0]
	v_pk_fma_f32 v[78:79], v[78:79], s[26:27], v[126:127] op_sel_hi:[1,0,0]
	v_pk_add_f32 v[76:77], v[76:77], 1.0 op_sel_hi:[1,0]
	v_pk_add_f32 v[70:71], v[70:71], 1.0 op_sel_hi:[1,0]
	v_pk_fma_f32 v[68:69], v[68:69], s[26:27], v[126:127] op_sel_hi:[1,0,0]
	v_max_f32_e32 v67, 0x4b000001, v67
	v_max_f32_e32 v66, 0x4b000001, v66
	v_pk_add_f32 v[80:81], v[80:81], 1.0 op_sel_hi:[1,0]
	v_max_f32_e32 v79, 0x4b000001, v79
	v_max_f32_e32 v78, 0x4b000001, v78
	v_pk_add_f32 v[74:75], v[74:75], 1.0 op_sel_hi:[1,0]
	v_rcp_f32_e32 v76, v76
	v_rcp_f32_e32 v77, v77
	v_pk_add_f32 v[72:73], v[72:73], 1.0 op_sel_hi:[1,0]
	v_rcp_f32_e32 v70, v70
	v_rcp_f32_e32 v71, v71
	v_perm_b32 v66, v67, v66, s58
	v_max_f32_e32 v67, 0x4b000001, v69
	v_max_f32_e32 v68, 0x4b000001, v68
	v_rcp_f32_e32 v80, v80
	v_rcp_f32_e32 v81, v81
	v_perm_b32 v84, v79, v78, s58
	v_rcp_f32_e32 v78, v74
	v_rcp_f32_e32 v79, v75
	v_rcp_f32_e32 v72, v72
	v_rcp_f32_e32 v73, v73
	v_perm_b32 v67, v67, v68, s58
	v_pk_fma_f32 v[76:77], v[76:77], s[26:27], v[126:127] op_sel_hi:[1,0,0]
	v_pk_fma_f32 v[70:71], v[70:71], s[26:27], v[126:127] op_sel_hi:[1,0,0]
	v_pk_fma_f32 v[80:81], v[80:81], s[26:27], v[126:127] op_sel_hi:[1,0,0]
	v_pk_fma_f32 v[78:79], v[78:79], s[26:27], v[126:127] op_sel_hi:[1,0,0]
	v_max_f32_e32 v77, 0x4b000001, v77
	v_max_f32_e32 v76, 0x4b000001, v76
	v_pk_fma_f32 v[72:73], v[72:73], s[26:27], v[126:127] op_sel_hi:[1,0,0]
	v_max_f32_e32 v71, 0x4b000001, v71
	v_max_f32_e32 v70, 0x4b000001, v70
	v_mad_i64_i32 v[82:83], s[2:3], v192, s57, v[142:143]
	v_max_f32_e32 v81, 0x4b000001, v81
	v_max_f32_e32 v80, 0x4b000001, v80
	v_max_f32_e32 v75, 0x4b000001, v79
	v_max_f32_e32 v78, 0x4b000001, v78
	v_perm_b32 v76, v77, v76, s58
	v_perm_b32 v70, v71, v70, s58
	v_max_f32_e32 v71, 0x4b000001, v73
	v_max_f32_e32 v72, 0x4b000001, v72
	v_lshl_or_b32 v77, v67, 16, v66
	v_lshl_add_u64 v[82:83], v[82:83], 0, s[0:1]
	v_perm_b32 v74, v81, v80, s58
	v_perm_b32 v75, v75, v78, s58
	v_perm_b32 v71, v71, v72, s58
;     __device__ __forceinline__ void operator()(const f32x4 (&acc)[2][2][4][2], const Unit& u, int wr, int wc, int fr, int fq) const {
;     ...
; #pragma unroll
;         for (int ai = 0; ai < 2; ++ai)
; #pragma unroll
;             for (int m = 0; m < 4; ++m) { unsigned char* rowp = O + (size_t)(row0 + ai * HALF + m * 16) * 8704 + gbase + (col0 & 1023);
;                 const float rs = rsv[ai * 4 + m];
;                 u32x4 w; EPG_Q4(w.x, acc[ai][0][m][0], wv[0][0], rs, bv[0][0]); EPG_Q4(w.y, acc[ai][0][m][1], wv[0][1], rs, bv[0][1]);
;                 EPG_Q4(w.z, acc[ai][1][m][0], wv[1][0], rs, bv[1][0]); EPG_Q4(w.w, acc[ai][1][m][1], wv[1][1], rs, bv[1][1]);
;                 *(u32x4*)rowp = w; }
	v_lshl_add_u64 v[82:83], v[82:83], 0, v[154:155]
	v_lshl_or_b32 v74, v74, 16, v84
	v_lshl_or_b32 v75, v76, 16, v75
	v_lshl_or_b32 v76, v71, 16, v70
	global_store_dwordx4 v[82:83], v[74:77], off
	v_pk_mul_f32 v[50:51], v[130:131], v[50:51]
	v_pk_mul_f32 v[62:63], v[174:175], v[62:63]
	v_pk_mul_f32 v[52:53], v[132:133], v[52:53]
	v_pk_fma_f32 v[50:51], v[50:51], v[182:183], v[128:129] op_sel_hi:[1,0,1]
	v_pk_fma_f32 v[62:63], v[62:63], v[182:183], v[172:173] op_sel_hi:[1,0,1]
	v_pk_fma_f32 v[52:53], v[52:53], v[182:183], v[124:125] op_sel_hi:[1,0,1]
	v_exp_f32_e32 v50, v50
	v_exp_f32_e32 v51, v51
	v_exp_f32_e32 v62, v62
	v_exp_f32_e32 v63, v63
	v_exp_f32_e32 v52, v52
	v_exp_f32_e32 v53, v53
	v_pk_mul_f32 v[60:61], v[168:169], v[60:61]
	v_pk_mul_f32 v[54:55], v[138:139], v[54:55]
	v_pk_add_f32 v[50:51], v[50:51], 1.0 op_sel_hi:[1,0]
	v_pk_mul_f32 v[64:65], v[176:177], v[64:65]
	v_pk_add_f32 v[62:63], v[62:63], 1.0 op_sel_hi:[1,0]
	v_pk_mul_f32 v[58:59], v[166:167], v[58:59]
	v_pk_fma_f32 v[60:61], v[60:61], v[182:183], v[144:145] op_sel_hi:[1,0,1]
	v_pk_mul_f32 v[56:57], v[140:141], v[56:57]
	v_pk_fma_f32 v[54:55], v[54:55], v[182:183], v[136:137] op_sel_hi:[1,0,1]
	v_pk_add_f32 v[52:53], v[52:53], 1.0 op_sel_hi:[1,0]
	v_rcp_f32_e32 v50, v50
	v_rcp_f32_e32 v51, v51
	v_pk_fma_f32 v[64:65], v[64:65], v[182:183], v[170:171] op_sel_hi:[1,0,1]
	v_rcp_f32_e32 v62, v62
	v_rcp_f32_e32 v63, v63
	v_pk_fma_f32 v[58:59], v[58:59], v[182:183], v[164:165] op_sel_hi:[1,0,1]
	v_exp_f32_e32 v60, v60
	v_exp_f32_e32 v61, v61
	v_pk_fma_f32 v[56:57], v[56:57], v[182:183], v[134:135] op_sel_hi:[1,0,1]
	v_exp_f32_e32 v54, v54
	v_exp_f32_e32 v55, v55
	v_rcp_f32_e32 v52, v52
	v_rcp_f32_e32 v53, v53
	v_exp_f32_e32 v64, v64
	v_exp_f32_e32 v65, v65
	v_exp_f32_e32 v58, v58
	v_exp_f32_e32 v59, v59
	v_exp_f32_e32 v56, v56
	v_exp_f32_e32 v57, v57
	v_pk_fma_f32 v[50:51], v[50:51], s[26:27], v[126:127] op_sel_hi:[1,0,0]
	v_pk_fma_f32 v[62:63], v[62:63], s[26:27], v[126:127] op_sel_hi:[1,0,0]
	v_pk_add_f32 v[60:61], v[60:61], 1.0 op_sel_hi:[1,0]
	v_pk_add_f32 v[54:55], v[54:55], 1.0 op_sel_hi:[1,0]
	v_pk_fma_f32 v[52:53], v[52:53], s[26:27], v[126:127] op_sel_hi:[1,0,0]
	v_max_f32_e32 v51, 0x4b000001, v51
	v_max_f32_e32 v50, 0x4b000001, v50
	v_pk_add_f32 v[64:65], v[64:65], 1.0 op_sel_hi:[1,0]
	v_max_f32_e32 v63, 0x4b000001, v63
	v_max_f32_e32 v62, 0x4b000001, v62
	v_pk_add_f32 v[58:59], v[58:59], 1.0 op_sel_hi:[1,0]
	v_rcp_f32_e32 v60, v60
	v_rcp_f32_e32 v61, v61
	v_pk_add_f32 v[56:57], v[56:57], 1.0 op_sel_hi:[1,0]
	v_rcp_f32_e32 v54, v54
	v_rcp_f32_e32 v55, v55
	v_perm_b32 v50, v51, v50, s58
	v_max_f32_e32 v51, 0x4b000001, v53
	v_max_f32_e32 v52, 0x4b000001, v52
	v_rcp_f32_e32 v64, v64
	v_rcp_f32_e32 v65, v65
	v_perm_b32 v68, v63, v62, s58
	v_rcp_f32_e32 v62, v58
	v_rcp_f32_e32 v63, v59
	v_rcp_f32_e32 v56, v56
	v_rcp_f32_e32 v57, v57
	v_perm_b32 v51, v51, v52, s58
	v_pk_fma_f32 v[60:61], v[60:61], s[26:27], v[126:127] op_sel_hi:[1,0,0]
	v_pk_fma_f32 v[54:55], v[54:55], s[26:27], v[126:127] op_sel_hi:[1,0,0]
	v_pk_fma_f32 v[64:65], v[64:65], s[26:27], v[126:127] op_sel_hi:[1,0,0]
	v_pk_fma_f32 v[62:63], v[62:63], s[26:27], v[126:127] op_sel_hi:[1,0,0]
	v_max_f32_e32 v61, 0x4b000001, v61
	v_max_f32_e32 v60, 0x4b000001, v60
	v_pk_fma_f32 v[56:57], v[56:57], s[26:27], v[126:127] op_sel_hi:[1,0,0]
	v_max_f32_e32 v55, 0x4b000001, v55
	v_max_f32_e32 v54, 0x4b000001, v54
	v_mad_i64_i32 v[66:67], s[2:3], v191, s57, v[142:143]
	v_max_f32_e32 v65, 0x4b000001, v65
	v_max_f32_e32 v64, 0x4b000001, v64
	v_max_f32_e32 v59, 0x4b000001, v63
	v_max_f32_e32 v62, 0x4b000001, v62
	v_perm_b32 v60, v61, v60, s58
	v_perm_b32 v54, v55, v54, s58
	v_max_f32_e32 v55, 0x4b000001, v57
	v_max_f32_e32 v56, 0x4b000001, v56
	v_lshl_or_b32 v61, v51, 16, v50
	v_lshl_add_u64 v[66:67], v[66:67], 0, s[0:1]
	v_perm_b32 v58, v65, v64, s58
	v_perm_b32 v59, v59, v62, s58
	v_perm_b32 v55, v55, v56, s58
	v_lshl_add_u64 v[66:67], v[66:67], 0, v[154:155]
	v_lshl_or_b32 v58, v58, 16, v68
	v_lshl_or_b32 v59, v60, 16, v59
	v_lshl_or_b32 v60, v55, 16, v54
	global_store_dwordx4 v[66:67], v[58:61], off
	v_pk_mul_f32 v[34:35], v[130:131], v[34:35]
	v_pk_mul_f32 v[46:47], v[174:175], v[46:47]
	v_pk_mul_f32 v[36:37], v[132:133], v[36:37]
	v_pk_fma_f32 v[34:35], v[34:35], v[180:181], v[128:129] op_sel_hi:[1,0,1]
	v_pk_fma_f32 v[46:47], v[46:47], v[180:181], v[172:173] op_sel_hi:[1,0,1]
	v_pk_fma_f32 v[36:37], v[36:37], v[180:181], v[124:125] op_sel_hi:[1,0,1]
	v_exp_f32_e32 v34, v34
	v_exp_f32_e32 v35, v35
	v_exp_f32_e32 v46, v46
	v_exp_f32_e32 v47, v47
	v_exp_f32_e32 v36, v36
	v_exp_f32_e32 v37, v37
	v_pk_mul_f32 v[44:45], v[168:169], v[44:45]
	v_pk_mul_f32 v[38:39], v[138:139], v[38:39]
	v_pk_add_f32 v[34:35], v[34:35], 1.0 op_sel_hi:[1,0]
	v_pk_mul_f32 v[48:49], v[176:177], v[48:49]
	v_pk_add_f32 v[46:47], v[46:47], 1.0 op_sel_hi:[1,0]
	v_pk_mul_f32 v[42:43], v[166:167], v[42:43]
	v_pk_fma_f32 v[44:45], v[44:45], v[180:181], v[144:145] op_sel_hi:[1,0,1]
	v_pk_mul_f32 v[40:41], v[140:141], v[40:41]
	v_pk_fma_f32 v[38:39], v[38:39], v[180:181], v[136:137] op_sel_hi:[1,0,1]
	v_pk_add_f32 v[36:37], v[36:37], 1.0 op_sel_hi:[1,0]
	v_rcp_f32_e32 v34, v34
	v_rcp_f32_e32 v35, v35
	v_pk_fma_f32 v[48:49], v[48:49], v[180:181], v[170:171] op_sel_hi:[1,0,1]
	v_rcp_f32_e32 v46, v46
	v_rcp_f32_e32 v47, v47
	v_pk_fma_f32 v[42:43], v[42:43], v[180:181], v[164:165] op_sel_hi:[1,0,1]
	v_exp_f32_e32 v44, v44
	v_exp_f32_e32 v45, v45
	v_pk_fma_f32 v[40:41], v[40:41], v[180:181], v[134:135] op_sel_hi:[1,0,1]
	v_exp_f32_e32 v38, v38
	v_exp_f32_e32 v39, v39
	v_rcp_f32_e32 v36, v36
	v_rcp_f32_e32 v37, v37
	v_exp_f32_e32 v48, v48
	v_exp_f32_e32 v49, v49
;     __device__ __forceinline__ void operator()(const f32x4 (&acc)[2][2][4][2], const Unit& u, int wr, int wc, int fr, int fq) const {
;     ...
; #pragma unroll
;         for (int ai = 0; ai < 2; ++ai)
; #pragma unroll
;             for (int m = 0; m < 4; ++m) { unsigned char* rowp = O + (size_t)(row0 + ai * HALF + m * 16) * 8704 + gbase + (col0 & 1023);
;                 const float rs = rsv[ai * 4 + m];
;                 u32x4 w; EPG_Q4(w.x, acc[ai][0][m][0], wv[0][0], rs, bv[0][0]); EPG_Q4(w.y, acc[ai][0][m][1], wv[0][1], rs, bv[0][1]);
;                 EPG_Q4(w.z, acc[ai][1][m][0], wv[1][0], rs, bv[1][0]); EPG_Q4(w.w, acc[ai][1][m][1], wv[1][1], rs, bv[1][1]);
;                 *(u32x4*)rowp = w; }
	v_exp_f32_e32 v42, v42
	v_exp_f32_e32 v43, v43
	v_exp_f32_e32 v40, v40
	v_exp_f32_e32 v41, v41
	v_pk_fma_f32 v[34:35], v[34:35], s[26:27], v[126:127] op_sel_hi:[1,0,0]
	v_pk_fma_f32 v[46:47], v[46:47], s[26:27], v[126:127] op_sel_hi:[1,0,0]
	v_pk_add_f32 v[44:45], v[44:45], 1.0 op_sel_hi:[1,0]
	v_pk_add_f32 v[38:39], v[38:39], 1.0 op_sel_hi:[1,0]
	v_pk_fma_f32 v[36:37], v[36:37], s[26:27], v[126:127] op_sel_hi:[1,0,0]
	v_max_f32_e32 v35, 0x4b000001, v35
	v_max_f32_e32 v34, 0x4b000001, v34
	v_pk_add_f32 v[48:49], v[48:49], 1.0 op_sel_hi:[1,0]
	v_max_f32_e32 v47, 0x4b000001, v47
	v_max_f32_e32 v46, 0x4b000001, v46
	v_pk_add_f32 v[42:43], v[42:43], 1.0 op_sel_hi:[1,0]
	v_rcp_f32_e32 v44, v44
	v_rcp_f32_e32 v45, v45
	v_pk_add_f32 v[40:41], v[40:41], 1.0 op_sel_hi:[1,0]
	v_rcp_f32_e32 v38, v38
	v_rcp_f32_e32 v39, v39
	v_perm_b32 v34, v35, v34, s58
	v_max_f32_e32 v35, 0x4b000001, v37
	v_max_f32_e32 v36, 0x4b000001, v36
	v_rcp_f32_e32 v48, v48
	v_rcp_f32_e32 v49, v49
	v_perm_b32 v52, v47, v46, s58
	v_rcp_f32_e32 v46, v42
	v_rcp_f32_e32 v47, v43
	v_rcp_f32_e32 v40, v40
	v_rcp_f32_e32 v41, v41
	v_perm_b32 v35, v35, v36, s58
	v_pk_fma_f32 v[44:45], v[44:45], s[26:27], v[126:127] op_sel_hi:[1,0,0]
	v_pk_fma_f32 v[38:39], v[38:39], s[26:27], v[126:127] op_sel_hi:[1,0,0]
	v_pk_fma_f32 v[48:49], v[48:49], s[26:27], v[126:127] op_sel_hi:[1,0,0]
	v_pk_fma_f32 v[46:47], v[46:47], s[26:27], v[126:127] op_sel_hi:[1,0,0]
	v_max_f32_e32 v45, 0x4b000001, v45
	v_max_f32_e32 v44, 0x4b000001, v44
	v_pk_fma_f32 v[40:41], v[40:41], s[26:27], v[126:127] op_sel_hi:[1,0,0]
	v_max_f32_e32 v39, 0x4b000001, v39
	v_max_f32_e32 v38, 0x4b000001, v38
	v_mad_i64_i32 v[50:51], s[2:3], v190, s57, v[142:143]
	v_max_f32_e32 v49, 0x4b000001, v49
	v_max_f32_e32 v48, 0x4b000001, v48
	v_max_f32_e32 v43, 0x4b000001, v47
	v_max_f32_e32 v46, 0x4b000001, v46
	v_perm_b32 v44, v45, v44, s58
	v_perm_b32 v38, v39, v38, s58
	v_max_f32_e32 v39, 0x4b000001, v41
	v_max_f32_e32 v40, 0x4b000001, v40
	v_lshl_or_b32 v45, v35, 16, v34
	v_lshl_add_u64 v[50:51], v[50:51], 0, s[0:1]
	v_perm_b32 v42, v49, v48, s58
	v_perm_b32 v43, v43, v46, s58
	v_perm_b32 v39, v39, v40, s58
	v_lshl_add_u64 v[50:51], v[50:51], 0, v[154:155]
	v_lshl_or_b32 v42, v42, 16, v52
	v_lshl_or_b32 v43, v44, 16, v43
	v_lshl_or_b32 v44, v39, 16, v38
	global_store_dwordx4 v[50:51], v[42:45], off
	v_pk_mul_f32 v[18:19], v[130:131], v[18:19]
	v_pk_mul_f32 v[30:31], v[174:175], v[30:31]
	v_pk_mul_f32 v[20:21], v[132:133], v[20:21]
	v_pk_fma_f32 v[18:19], v[18:19], v[178:179], v[128:129] op_sel_hi:[1,0,1]
	v_pk_fma_f32 v[30:31], v[30:31], v[178:179], v[172:173] op_sel_hi:[1,0,1]
	v_pk_fma_f32 v[20:21], v[20:21], v[178:179], v[124:125] op_sel_hi:[1,0,1]
	v_exp_f32_e32 v18, v18
	v_exp_f32_e32 v19, v19
	v_exp_f32_e32 v30, v30
	v_exp_f32_e32 v31, v31
	v_exp_f32_e32 v20, v20
	v_exp_f32_e32 v21, v21
	v_pk_mul_f32 v[28:29], v[168:169], v[28:29]
	v_pk_mul_f32 v[22:23], v[138:139], v[22:23]
	v_pk_add_f32 v[18:19], v[18:19], 1.0 op_sel_hi:[1,0]
	v_pk_mul_f32 v[32:33], v[176:177], v[32:33]
	v_pk_add_f32 v[30:31], v[30:31], 1.0 op_sel_hi:[1,0]
	v_pk_mul_f32 v[26:27], v[166:167], v[26:27]
	v_pk_fma_f32 v[28:29], v[28:29], v[178:179], v[144:145] op_sel_hi:[1,0,1]
	v_pk_mul_f32 v[24:25], v[140:141], v[24:25]
	v_pk_fma_f32 v[22:23], v[22:23], v[178:179], v[136:137] op_sel_hi:[1,0,1]
	v_pk_add_f32 v[20:21], v[20:21], 1.0 op_sel_hi:[1,0]
	v_rcp_f32_e32 v18, v18
	v_rcp_f32_e32 v19, v19
	v_pk_fma_f32 v[32:33], v[32:33], v[178:179], v[170:171] op_sel_hi:[1,0,1]
	v_rcp_f32_e32 v30, v30
	v_rcp_f32_e32 v31, v31
	v_pk_fma_f32 v[26:27], v[26:27], v[178:179], v[164:165] op_sel_hi:[1,0,1]
	v_exp_f32_e32 v28, v28
	v_exp_f32_e32 v29, v29
	v_pk_fma_f32 v[24:25], v[24:25], v[178:179], v[134:135] op_sel_hi:[1,0,1]
	v_exp_f32_e32 v22, v22
	v_exp_f32_e32 v23, v23
	v_rcp_f32_e32 v20, v20
	v_rcp_f32_e32 v21, v21
	v_exp_f32_e32 v32, v32
	v_exp_f32_e32 v33, v33
	v_exp_f32_e32 v26, v26
	v_exp_f32_e32 v27, v27
	v_exp_f32_e32 v24, v24
	v_exp_f32_e32 v25, v25
	v_pk_fma_f32 v[18:19], v[18:19], s[26:27], v[126:127] op_sel_hi:[1,0,0]
	v_pk_fma_f32 v[30:31], v[30:31], s[26:27], v[126:127] op_sel_hi:[1,0,0]
	v_pk_add_f32 v[28:29], v[28:29], 1.0 op_sel_hi:[1,0]
	v_pk_add_f32 v[22:23], v[22:23], 1.0 op_sel_hi:[1,0]
	v_pk_fma_f32 v[20:21], v[20:21], s[26:27], v[126:127] op_sel_hi:[1,0,0]
	v_max_f32_e32 v19, 0x4b000001, v19
	v_max_f32_e32 v18, 0x4b000001, v18
	v_pk_add_f32 v[32:33], v[32:33], 1.0 op_sel_hi:[1,0]
	v_max_f32_e32 v31, 0x4b000001, v31
	v_max_f32_e32 v30, 0x4b000001, v30
	v_pk_add_f32 v[26:27], v[26:27], 1.0 op_sel_hi:[1,0]
	v_rcp_f32_e32 v28, v28
	v_rcp_f32_e32 v29, v29
	v_pk_add_f32 v[24:25], v[24:25], 1.0 op_sel_hi:[1,0]
	v_rcp_f32_e32 v22, v22
	v_rcp_f32_e32 v23, v23
	v_perm_b32 v18, v19, v18, s58
	v_max_f32_e32 v19, 0x4b000001, v21
	v_max_f32_e32 v20, 0x4b000001, v20
	v_rcp_f32_e32 v32, v32
	v_rcp_f32_e32 v33, v33
	v_perm_b32 v36, v31, v30, s58
	v_rcp_f32_e32 v30, v26
	v_rcp_f32_e32 v31, v27
	v_rcp_f32_e32 v24, v24
	v_rcp_f32_e32 v25, v25
	v_perm_b32 v19, v19, v20, s58
	v_pk_fma_f32 v[28:29], v[28:29], s[26:27], v[126:127] op_sel_hi:[1,0,0]
; #define PG8_BAR __builtin_amdgcn_s_barrier()
;     __device__ __forceinline__ void operator()(const f32x4 (&acc)[2][2][4][2], const Unit& u, int wr, int wc, int fr, int fq) const {
;     ...
; #pragma unroll
;         for (int ai = 0; ai < 2; ++ai)
; #pragma unroll
;             for (int m = 0; m < 4; ++m) { unsigned char* rowp = O + (size_t)(row0 + ai * HALF + m * 16) * 8704 + gbase + (col0 & 1023);
;                 const float rs = rsv[ai * 4 + m];
;                 u32x4 w; EPG_Q4(w.x, acc[ai][0][m][0], wv[0][0], rs, bv[0][0]); EPG_Q4(w.y, acc[ai][0][m][1], wv[0][1], rs, bv[0][1]);
;                 EPG_Q4(w.z, acc[ai][1][m][0], wv[1][0], rs, bv[1][0]); EPG_Q4(w.w, acc[ai][1][m][1], wv[1][1], rs, bv[1][1]);
;                 *(u32x4*)rowp = w; }
; template <class Epi, class Sched, class Gemm, bool ALIGN_EPI = false, bool SP2 = false>
; __device__ __forceinline__ void gemm_phase(PG8_LAS unsigned char* lds, const Gemm g, const Sched& S, const Epi& E) {
;     ...
;         if (!has_next) break;
;         if constexpr (!epi_chain<Epi>::value) {
; #pragma unroll
;         for (int a = 0; a < 2; ++a)
; #pragma unroll
;             for (int b = 0; b < 2; ++b)
; #pragma unroll
;                 for (int m = 0; m < 4; ++m)
; #pragma unroll
;                     for (int n = 0; n < 2; ++n) acc[a][b][m][n] = (f32x4){0.f, 0.f, 0.f, 0.f};
;         }
;         cur = nxt; cA = nA; cB = nB; ++ui;
;         if constexpr (ALIGN_EPI) { if (wr == 1) PG8_BAR; }
	v_pk_fma_f32 v[22:23], v[22:23], s[26:27], v[126:127] op_sel_hi:[1,0,0]
	v_pk_fma_f32 v[32:33], v[32:33], s[26:27], v[126:127] op_sel_hi:[1,0,0]
	v_pk_fma_f32 v[30:31], v[30:31], s[26:27], v[126:127] op_sel_hi:[1,0,0]
	v_max_f32_e32 v29, 0x4b000001, v29
	v_max_f32_e32 v28, 0x4b000001, v28
	v_pk_fma_f32 v[24:25], v[24:25], s[26:27], v[126:127] op_sel_hi:[1,0,0]
	v_max_f32_e32 v23, 0x4b000001, v23
	v_max_f32_e32 v22, 0x4b000001, v22
	v_mad_i64_i32 v[34:35], s[2:3], v189, s57, v[142:143]
	v_max_f32_e32 v33, 0x4b000001, v33
	v_max_f32_e32 v32, 0x4b000001, v32
	v_max_f32_e32 v27, 0x4b000001, v31
	v_max_f32_e32 v30, 0x4b000001, v30
	v_perm_b32 v28, v29, v28, s58
	v_perm_b32 v22, v23, v22, s58
	v_max_f32_e32 v23, 0x4b000001, v25
	v_max_f32_e32 v24, 0x4b000001, v24
	v_lshl_or_b32 v29, v19, 16, v18
	v_lshl_add_u64 v[34:35], v[34:35], 0, s[0:1]
	v_perm_b32 v26, v33, v32, s58
	v_perm_b32 v27, v27, v30, s58
	v_perm_b32 v23, v23, v24, s58
	v_lshl_add_u64 v[34:35], v[34:35], 0, v[154:155]
	v_lshl_or_b32 v26, v26, 16, v36
	v_lshl_or_b32 v27, v28, 16, v27
	v_lshl_or_b32 v28, v23, 16, v22
	global_store_dwordx4 v[34:35], v[26:29], off
	v_pk_mul_f32 v[14:15], v[174:175], v[14:15]
	v_pk_fma_f32 v[14:15], v[14:15], v[122:123], v[172:173] op_sel_hi:[1,0,1]
	v_exp_f32_e32 v14, v14
	v_exp_f32_e32 v15, v15
	v_pk_mul_f32 v[6:7], v[138:139], v[6:7]
	v_pk_mul_f32 v[2:3], v[130:131], v[2:3]
	v_pk_mul_f32 v[16:17], v[176:177], v[16:17]
	v_pk_add_f32 v[14:15], v[14:15], 1.0 op_sel_hi:[1,0]
	v_pk_mul_f32 v[12:13], v[168:169], v[12:13]
	v_pk_mul_f32 v[10:11], v[166:167], v[10:11]
	v_pk_mul_f32 v[8:9], v[140:141], v[8:9]
	v_pk_fma_f32 v[6:7], v[6:7], v[122:123], v[136:137] op_sel_hi:[1,0,1]
	v_pk_mul_f32 v[4:5], v[132:133], v[4:5]
	v_pk_fma_f32 v[2:3], v[2:3], v[122:123], v[128:129] op_sel_hi:[1,0,1]
	v_pk_fma_f32 v[16:17], v[16:17], v[122:123], v[170:171] op_sel_hi:[1,0,1]
	v_rcp_f32_e32 v14, v14
	v_rcp_f32_e32 v15, v15
	v_pk_fma_f32 v[12:13], v[12:13], v[122:123], v[144:145] op_sel_hi:[1,0,1]
	v_pk_fma_f32 v[10:11], v[10:11], v[122:123], v[164:165] op_sel_hi:[1,0,1]
	v_pk_fma_f32 v[8:9], v[8:9], v[122:123], v[134:135] op_sel_hi:[1,0,1]
	v_exp_f32_e32 v6, v6
	v_exp_f32_e32 v7, v7
	v_pk_fma_f32 v[4:5], v[4:5], v[122:123], v[124:125] op_sel_hi:[1,0,1]
	v_exp_f32_e32 v2, v2
	v_exp_f32_e32 v3, v3
	v_exp_f32_e32 v16, v16
	v_exp_f32_e32 v17, v17
	v_exp_f32_e32 v10, v10
	v_exp_f32_e32 v12, v12
	v_exp_f32_e32 v13, v13
	v_exp_f32_e32 v11, v11
	v_exp_f32_e32 v8, v8
	v_exp_f32_e32 v9, v9
	v_exp_f32_e32 v4, v4
	v_exp_f32_e32 v5, v5
	v_pk_fma_f32 v[14:15], v[14:15], s[26:27], v[126:127] op_sel_hi:[1,0,0]
	v_pk_add_f32 v[6:7], v[6:7], 1.0 op_sel_hi:[1,0]
	v_pk_add_f32 v[2:3], v[2:3], 1.0 op_sel_hi:[1,0]
	v_pk_add_f32 v[16:17], v[16:17], 1.0 op_sel_hi:[1,0]
	v_max_f32_e32 v15, 0x4b000001, v15
	v_max_f32_e32 v14, 0x4b000001, v14
	v_pk_add_f32 v[12:13], v[12:13], 1.0 op_sel_hi:[1,0]
	v_pk_add_f32 v[10:11], v[10:11], 1.0 op_sel_hi:[1,0]
	v_pk_add_f32 v[8:9], v[8:9], 1.0 op_sel_hi:[1,0]
	v_rcp_f32_e32 v6, v6
	v_rcp_f32_e32 v7, v7
	v_pk_add_f32 v[4:5], v[4:5], 1.0 op_sel_hi:[1,0]
	v_rcp_f32_e32 v2, v2
	v_rcp_f32_e32 v3, v3
	v_rcp_f32_e32 v16, v16
	v_rcp_f32_e32 v17, v17
	v_perm_b32 v20, v15, v14, s58
	v_rcp_f32_e32 v14, v10
	v_rcp_f32_e32 v12, v12
	v_rcp_f32_e32 v13, v13
	v_rcp_f32_e32 v15, v11
	v_rcp_f32_e32 v8, v8
	v_rcp_f32_e32 v9, v9
	v_rcp_f32_e32 v4, v4
	v_rcp_f32_e32 v5, v5
	v_pk_fma_f32 v[6:7], v[6:7], s[26:27], v[126:127] op_sel_hi:[1,0,0]
	v_pk_fma_f32 v[2:3], v[2:3], s[26:27], v[126:127] op_sel_hi:[1,0,0]
	v_pk_fma_f32 v[16:17], v[16:17], s[26:27], v[126:127] op_sel_hi:[1,0,0]
	v_pk_fma_f32 v[12:13], v[12:13], s[26:27], v[126:127] op_sel_hi:[1,0,0]
	v_pk_fma_f32 v[14:15], v[14:15], s[26:27], v[126:127] op_sel_hi:[1,0,0]
	v_pk_fma_f32 v[8:9], v[8:9], s[26:27], v[126:127] op_sel_hi:[1,0,0]
	v_max_f32_e32 v7, 0x4b000001, v7
	v_max_f32_e32 v6, 0x4b000001, v6
	v_pk_fma_f32 v[4:5], v[4:5], s[26:27], v[126:127] op_sel_hi:[1,0,0]
	v_max_f32_e32 v3, 0x4b000001, v3
	v_max_f32_e32 v2, 0x4b000001, v2
	v_mad_i64_i32 v[18:19], s[2:3], v123, s57, v[142:143]
	v_max_f32_e32 v17, 0x4b000001, v17
	v_max_f32_e32 v16, 0x4b000001, v16
	v_max_f32_e32 v11, 0x4b000001, v15
	v_max_f32_e32 v14, 0x4b000001, v14
	v_max_f32_e32 v13, 0x4b000001, v13
	v_max_f32_e32 v12, 0x4b000001, v12
	v_perm_b32 v6, v7, v6, s58
	v_max_f32_e32 v7, 0x4b000001, v9
	v_max_f32_e32 v8, 0x4b000001, v8
	v_perm_b32 v2, v3, v2, s58
	v_max_f32_e32 v3, 0x4b000001, v5
	v_max_f32_e32 v4, 0x4b000001, v4
	v_lshl_add_u64 v[18:19], v[18:19], 0, s[0:1]
	v_perm_b32 v10, v17, v16, s58
	v_perm_b32 v11, v11, v14, s58
	v_perm_b32 v12, v13, v12, s58
	v_perm_b32 v7, v7, v8, s58
	v_perm_b32 v3, v3, v4, s58
	v_lshl_add_u64 v[18:19], v[18:19], 0, v[154:155]
	v_lshl_or_b32 v10, v10, 16, v20
	v_lshl_or_b32 v11, v12, 16, v11
	v_lshl_or_b32 v12, v7, 16, v6
	v_lshl_or_b32 v13, v3, 16, v2
	global_store_dwordx4 v[18:19], v[10:13], off
	s_andn2_b64 vcc, exec, s[4:5]
	s_mov_b64 s[0:1], -1
	s_cbranch_vccnz .LBB0_1184
	s_andn2_b64 vcc, exec, s[6:7]
	s_cbranch_vccnz .LBB0_1183
	s_barrier
	s_branch .LBB0_1183

;     __device__ __forceinline__ void operator()(const f32x4 (&acc)[2][2][4][2], const Unit& u, int wr, int wc, int fr, int fq) const {
;     ...
;         const int row0 = u.pm * BM + wr * 64 + fr, col0 = u.pn * BM + wc * 64 + 16 * fq;
;         const int gn = u.pn >> 2, gbase = (gn < 3) ? 3072 + 1024 * gn : 0;
;         f32x4 bv[2][2];
; #pragma unroll
;         for (int bj = 0; bj < 2; ++bj)
; #pragma unroll
;             for (int n = 0; n < 2; ++n) bv[bj][n] = *(const f32x4*)(bias + col0 + 8 * bj + 4 * n) * -1.44269504f;
;         f32x4 wv[2][2];
; #pragma unroll
;         for (int bj = 0; bj < 2; ++bj)
; #pragma unroll
;             for (int n = 0; n < 2; ++n) wv[bj][n] = *(const f32x4*)(SW + col0 + 8 * bj + 4 * n) * -1.44269504f;
;         float rsv[8];
; #pragma unroll
;         for (int i = 0; i < 8; ++i) rsv[i] = SH[row0 + (i >> 2) * HALF + (i & 3) * 16];
;     ...
; #pragma unroll
;         for (int ai = 0; ai < 2; ++ai)
; #pragma unroll
;             for (int m = 0; m < 4; ++m) { unsigned char* rowp = O + (size_t)(row0 + ai * HALF + m * 16) * 8704 + gbase + (col0 & 1023);
;                 const float rs = rsv[ai * 4 + m];
;                 u32x4 w; EPG_Q4(w.x, acc[ai][0][m][0], wv[0][0], rs, bv[0][0]); EPG_Q4(w.y, acc[ai][0][m][1], wv[0][1], rs, bv[0][1]);
.LBB0_2555:
	s_lshl_b32 s0, s59, 8
	v_mov_b32_e32 v154, v1
	v_mov_b32_e32 v130, v179
	s_or_b32 s0, s0, s53
	v_cvt_f32_i32_e32 v212, v122
	v_lshl_add_u32 v144, v130, 4, s0
	s_lshl_b32 s0, s38, 8
	v_ashrrev_i32_e32 v145, 31, v144
	s_add_i32 s0, s0, s50
	v_lshlrev_b64 v[142:143], 2, v[144:145]
	v_add_u32_e32 v164, s0, v154
	v_lshl_add_u64 v[160:161], s[14:15], 0, v[142:143]
	v_ashrrev_i32_e32 v165, 31, v164
	global_load_dwordx4 v[130:133], v[160:161], off
	global_load_dwordx4 v[134:137], v[160:161], off offset:16
	global_load_dwordx4 v[138:141], v[160:161], off offset:32
	s_nop 0
	global_load_dwordx4 v[160:163], v[160:161], off offset:48
	v_lshl_add_u64 v[142:143], s[16:17], 0, v[142:143]
	v_lshl_add_u64 v[170:171], v[164:165], 2, s[12:13]
	global_load_dwordx4 v[166:169], v[142:143], off
	global_load_dwordx4 v[194:197], v[142:143], off offset:16
	global_load_dwordx4 v[198:201], v[142:143], off offset:32
	global_load_dwordx4 v[202:205], v[142:143], off offset:48
	global_load_dword v206, v[170:171], off
	global_load_dword v188, v[170:171], off offset:64
	global_load_dword v186, v[170:171], off offset:128
	global_load_dword v184, v[170:171], off offset:192
	global_load_dword v182, v[170:171], off offset:512
	global_load_dword v180, v[170:171], off offset:576
	global_load_dword v178, v[170:171], off offset:640
	global_load_dword v122, v[170:171], off offset:704
	s_ashr_i32 s0, s59, 2
	s_lshl_b32 s1, s0, 10
	v_mov_b64_e32 v[142:143], s[10:11]
	s_add_i32 s2, s1, 0xc00
	v_cvt_f32_i32_e32 v209, v127
	v_cvt_f32_i32_e32 v208, v126
	v_cvt_f32_i32_e32 v215, v125
	v_cvt_f32_i32_e32 v214, v124
	s_cmp_lt_i32 s0, 3
	v_mad_i64_i32 v[124:125], s[0:1], v164, s57, v[142:143]
	s_cselect_b32 s0, s2, 0
	v_cvt_f32_i32_e32 v211, v129
	v_cvt_f32_i32_e32 v210, v128
	s_ashr_i32 s1, s0, 31
	v_cvt_f32_i32_e32 v115, v115
	v_cvt_f32_i32_e32 v114, v114
	v_cvt_f32_i32_e32 v99, v99
	v_cvt_f32_i32_e32 v98, v98
	v_cvt_f32_i32_e32 v83, v83
	v_cvt_f32_i32_e32 v82, v82
	v_cvt_f32_i32_e32 v67, v67
	v_cvt_f32_i32_e32 v66, v66
	v_cvt_f32_i32_e32 v51, v51
	v_cvt_f32_i32_e32 v50, v50
	v_cvt_f32_i32_e32 v35, v35
	v_cvt_f32_i32_e32 v34, v34
	v_cvt_f32_i32_e32 v19, v19
	v_cvt_f32_i32_e32 v18, v18
	v_and_b32_e32 v154, 0x3f0, v144
	v_lshl_add_u64 v[124:125], v[124:125], 0, s[0:1]
	v_cvt_f32_i32_e32 v117, v117
	v_cvt_f32_i32_e32 v116, v116
	v_cvt_f32_i32_e32 v111, v111
	v_cvt_f32_i32_e32 v110, v110
	v_cvt_f32_i32_e32 v101, v101
	v_cvt_f32_i32_e32 v100, v100
	v_cvt_f32_i32_e32 v95, v95
	v_cvt_f32_i32_e32 v94, v94
	v_cvt_f32_i32_e32 v85, v85
	v_cvt_f32_i32_e32 v84, v84
	v_cvt_f32_i32_e32 v79, v79
	v_cvt_f32_i32_e32 v78, v78
	v_cvt_f32_i32_e32 v69, v69
	v_cvt_f32_i32_e32 v68, v68
	v_cvt_f32_i32_e32 v63, v63
	v_cvt_f32_i32_e32 v62, v62
	v_cvt_f32_i32_e32 v53, v53
	v_cvt_f32_i32_e32 v52, v52
	v_cvt_f32_i32_e32 v47, v47
	v_cvt_f32_i32_e32 v46, v46
	v_cvt_f32_i32_e32 v37, v37
	v_cvt_f32_i32_e32 v36, v36
	v_cvt_f32_i32_e32 v31, v31
	v_cvt_f32_i32_e32 v30, v30
	v_cvt_f32_i32_e32 v21, v21
	v_cvt_f32_i32_e32 v20, v20
	v_cvt_f32_i32_e32 v15, v15
	v_cvt_f32_i32_e32 v14, v14
	v_add_u32_e32 v207, 32, v164
	v_lshl_add_u64 v[216:217], v[124:125], 0, v[154:155]
	v_add_u32_e32 v189, 0xa0, v164
	v_cvt_f32_i32_e32 v213, v123
	v_add_u32_e32 v123, 0xb0, v164
	v_cvt_f32_i32_e32 v119, v119
	v_cvt_f32_i32_e32 v118, v118
	v_cvt_f32_i32_e32 v109, v109
	v_cvt_f32_i32_e32 v108, v108
	v_cvt_f32_i32_e32 v103, v103
	v_cvt_f32_i32_e32 v102, v102
	v_cvt_f32_i32_e32 v93, v93
	v_cvt_f32_i32_e32 v121, v121
	v_cvt_f32_i32_e32 v120, v120
	v_cvt_f32_i32_e32 v113, v113
	v_cvt_f32_i32_e32 v112, v112
	v_cvt_f32_i32_e32 v107, v107
	v_cvt_f32_i32_e32 v106, v106
	v_cvt_f32_i32_e32 v105, v105
	v_cvt_f32_i32_e32 v104, v104
	v_cvt_f32_i32_e32 v92, v92
	v_cvt_f32_i32_e32 v87, v87
	v_cvt_f32_i32_e32 v86, v86
	v_cvt_f32_i32_e32 v97, v97
	v_cvt_f32_i32_e32 v96, v96
	v_cvt_f32_i32_e32 v91, v91
	v_cvt_f32_i32_e32 v90, v90
	v_cvt_f32_i32_e32 v89, v89
	v_cvt_f32_i32_e32 v88, v88
	v_cvt_f32_i32_e32 v77, v77
	v_cvt_f32_i32_e32 v76, v76
	v_cvt_f32_i32_e32 v71, v71
	v_cvt_f32_i32_e32 v70, v70
	v_cvt_f32_i32_e32 v81, v81
	v_cvt_f32_i32_e32 v80, v80
	v_cvt_f32_i32_e32 v75, v75
	v_cvt_f32_i32_e32 v74, v74
	v_cvt_f32_i32_e32 v73, v73
	v_cvt_f32_i32_e32 v72, v72
	v_cvt_f32_i32_e32 v61, v61
	v_cvt_f32_i32_e32 v60, v60
	v_cvt_f32_i32_e32 v55, v55
	v_cvt_f32_i32_e32 v54, v54
	v_cvt_f32_i32_e32 v65, v65
	v_cvt_f32_i32_e32 v64, v64
	v_cvt_f32_i32_e32 v59, v59
	v_cvt_f32_i32_e32 v58, v58
	v_cvt_f32_i32_e32 v57, v57
	v_cvt_f32_i32_e32 v56, v56
	v_cvt_f32_i32_e32 v45, v45
	v_cvt_f32_i32_e32 v44, v44
	v_cvt_f32_i32_e32 v39, v39
	v_cvt_f32_i32_e32 v38, v38
	v_cvt_f32_i32_e32 v49, v49
	v_cvt_f32_i32_e32 v48, v48
	v_cvt_f32_i32_e32 v43, v43
	v_cvt_f32_i32_e32 v42, v42
	v_cvt_f32_i32_e32 v41, v41
	v_cvt_f32_i32_e32 v40, v40
	v_cvt_f32_i32_e32 v29, v29
	v_cvt_f32_i32_e32 v28, v28
	v_cvt_f32_i32_e32 v23, v23
	v_cvt_f32_i32_e32 v22, v22
	v_cvt_f32_i32_e32 v33, v33
	v_cvt_f32_i32_e32 v32, v32
	v_cvt_f32_i32_e32 v27, v27
	v_cvt_f32_i32_e32 v26, v26
	v_cvt_f32_i32_e32 v25, v25
	v_cvt_f32_i32_e32 v24, v24
	v_cvt_f32_i32_e32 v7, v7
	v_cvt_f32_i32_e32 v6, v6
	v_cvt_f32_i32_e32 v3, v3
	v_cvt_f32_i32_e32 v2, v2
	v_cvt_f32_i32_e32 v17, v17
	v_cvt_f32_i32_e32 v16, v16
	v_cvt_f32_i32_e32 v11, v11
	v_cvt_f32_i32_e32 v13, v13
	v_cvt_f32_i32_e32 v12, v12
	v_cvt_f32_i32_e32 v10, v10
	v_cvt_f32_i32_e32 v9, v9
	v_cvt_f32_i32_e32 v8, v8
	v_cvt_f32_i32_e32 v5, v5
	v_cvt_f32_i32_e32 v4, v4
	s_waitcnt vmcnt(0)
;     __device__ __forceinline__ void operator()(const f32x4 (&acc)[2][2][4][2], const Unit& u, int wr, int wc, int fr, int fq) const {
;     ...
; #pragma unroll
;         for (int ai = 0; ai < 2; ++ai)
; #pragma unroll
;             for (int m = 0; m < 4; ++m) { unsigned char* rowp = O + (size_t)(row0 + ai * HALF + m * 16) * 8704 + gbase + (col0 & 1023);
;                 const float rs = rsv[ai * 4 + m];
;                 u32x4 w; EPG_Q4(w.x, acc[ai][0][m][0], wv[0][0], rs, bv[0][0]); EPG_Q4(w.y, acc[ai][0][m][1], wv[0][1], rs, bv[0][1]);
;                 EPG_Q4(w.z, acc[ai][1][m][0], wv[1][0], rs, bv[1][0]); EPG_Q4(w.w, acc[ai][1][m][1], wv[1][1], rs, bv[1][1]);
;                 *(u32x4*)rowp = w; }
	v_pk_mul_f32 v[172:173], v[130:131], s[22:23] op_sel_hi:[1,0]
	v_pk_mul_f32 v[170:171], v[132:133], s[22:23] op_sel_hi:[1,0]
	v_pk_mul_f32 v[174:175], v[166:167], s[22:23] op_sel_hi:[1,0]
	v_pk_mul_f32 v[124:125], v[162:163], s[22:23] op_sel_hi:[1,0]
	v_pk_mul_f32 v[162:163], v[174:175], v[208:209]
	v_pk_mul_f32 v[176:177], v[168:169], s[22:23] op_sel_hi:[1,0]
	v_pk_mul_f32 v[130:131], v[202:203], s[22:23] op_sel_hi:[1,0]
	v_pk_fma_f32 v[162:163], v[162:163], v[206:207], v[172:173] op_sel_hi:[1,0,1]
	v_pk_mul_f32 v[128:129], v[160:161], s[22:23] op_sel_hi:[1,0]
	v_pk_mul_f32 v[132:133], v[204:205], s[22:23] op_sel_hi:[1,0]
	v_pk_mul_f32 v[160:161], v[176:177], v[210:211]
	v_exp_f32_e32 v162, v162
	v_exp_f32_e32 v163, v163
	v_pk_mul_f32 v[114:115], v[130:131], v[114:115]
	v_pk_fma_f32 v[160:161], v[160:161], v[206:207], v[170:171] op_sel_hi:[1,0,1]
	v_pk_mul_f32 v[116:117], v[132:133], v[116:117]
	v_pk_fma_f32 v[114:115], v[114:115], v[206:207], v[128:129] op_sel_hi:[1,0,1]
	v_exp_f32_e32 v160, v160
	v_exp_f32_e32 v161, v161
	v_pk_fma_f32 v[116:117], v[116:117], v[206:207], v[124:125] op_sel_hi:[1,0,1]
	v_exp_f32_e32 v114, v114
	v_exp_f32_e32 v115, v115
	v_exp_f32_e32 v116, v116
	v_exp_f32_e32 v117, v117
	v_pk_mul_f32 v[166:167], v[194:195], s[22:23] op_sel_hi:[1,0]
	v_pk_add_f32 v[162:163], v[162:163], 1.0 op_sel_hi:[1,0]
	v_add_u32_e32 v193, 16, v164
	v_add_u32_e32 v192, 48, v164
	v_add_u32_e32 v191, 0x80, v164
	v_add_u32_e32 v190, 0x90, v164
	v_pk_mul_f32 v[144:145], v[136:137], s[22:23] op_sel_hi:[1,0]
	v_pk_mul_f32 v[164:165], v[134:135], s[22:23] op_sel_hi:[1,0]
	v_pk_mul_f32 v[136:137], v[138:139], s[22:23] op_sel_hi:[1,0]
	v_pk_mul_f32 v[168:169], v[196:197], s[22:23] op_sel_hi:[1,0]
	v_pk_mul_f32 v[138:139], v[198:199], s[22:23] op_sel_hi:[1,0]
	v_pk_mul_f32 v[196:197], v[166:167], v[212:213]
	v_rcp_f32_e32 v162, v162
	v_rcp_f32_e32 v163, v163
	v_pk_mul_f32 v[134:135], v[140:141], s[22:23] op_sel_hi:[1,0]
	v_pk_mul_f32 v[140:141], v[200:201], s[22:23] op_sel_hi:[1,0]
	v_pk_mul_f32 v[194:195], v[168:169], v[214:215]
	v_pk_fma_f32 v[196:197], v[196:197], v[206:207], v[164:165] op_sel_hi:[1,0,1]
	v_pk_add_f32 v[160:161], v[160:161], 1.0 op_sel_hi:[1,0]
	v_pk_mul_f32 v[118:119], v[138:139], v[118:119]
	v_pk_add_f32 v[114:115], v[114:115], 1.0 op_sel_hi:[1,0]
	v_pk_fma_f32 v[194:195], v[194:195], v[206:207], v[144:145] op_sel_hi:[1,0,1]
	v_exp_f32_e32 v196, v196
	v_rcp_f32_e32 v160, v160
	v_rcp_f32_e32 v161, v161
	v_exp_f32_e32 v197, v197
	v_pk_mul_f32 v[120:121], v[140:141], v[120:121]
	v_pk_fma_f32 v[118:119], v[118:119], v[206:207], v[136:137] op_sel_hi:[1,0,1]
	v_pk_add_f32 v[116:117], v[116:117], 1.0 op_sel_hi:[1,0]
	v_rcp_f32_e32 v114, v114
	v_rcp_f32_e32 v115, v115
	v_mov_b64_e32 v[126:127], s[24:25]
	v_exp_f32_e32 v194, v194
	v_exp_f32_e32 v195, v195
	v_pk_fma_f32 v[120:121], v[120:121], v[206:207], v[134:135] op_sel_hi:[1,0,1]
	v_exp_f32_e32 v118, v118
	v_exp_f32_e32 v119, v119
	v_rcp_f32_e32 v116, v116
	v_rcp_f32_e32 v117, v117
	v_pk_fma_f32 v[162:163], v[162:163], s[26:27], v[126:127] op_sel_hi:[1,0,0]
	v_exp_f32_e32 v120, v120
	v_exp_f32_e32 v121, v121
	v_max_f32_e32 v163, 0x4b000001, v163
	v_max_f32_e32 v162, 0x4b000001, v162
	v_pk_fma_f32 v[160:161], v[160:161], s[26:27], v[126:127] op_sel_hi:[1,0,0]
	v_perm_b32 v198, v163, v162, s58
	v_pk_add_f32 v[162:163], v[196:197], 1.0 op_sel_hi:[1,0]
	v_pk_fma_f32 v[114:115], v[114:115], s[26:27], v[126:127] op_sel_hi:[1,0,0]
	v_max_f32_e32 v199, 0x4b000001, v161
	v_max_f32_e32 v200, 0x4b000001, v160
	v_pk_add_f32 v[160:161], v[194:195], 1.0 op_sel_hi:[1,0]
	v_rcp_f32_e32 v162, v162
	v_rcp_f32_e32 v163, v163
	v_pk_add_f32 v[118:119], v[118:119], 1.0 op_sel_hi:[1,0]
	v_pk_fma_f32 v[116:117], v[116:117], s[26:27], v[126:127] op_sel_hi:[1,0,0]
	v_max_f32_e32 v115, 0x4b000001, v115
	v_max_f32_e32 v114, 0x4b000001, v114
	v_rcp_f32_e32 v194, v160
	v_rcp_f32_e32 v195, v161
	v_pk_add_f32 v[120:121], v[120:121], 1.0 op_sel_hi:[1,0]
	v_rcp_f32_e32 v118, v118
	v_rcp_f32_e32 v119, v119
	v_perm_b32 v114, v115, v114, s58
	v_max_f32_e32 v115, 0x4b000001, v117
	v_max_f32_e32 v116, 0x4b000001, v116
	v_rcp_f32_e32 v120, v120
	v_rcp_f32_e32 v121, v121
	v_perm_b32 v115, v115, v116, s58
	v_pk_fma_f32 v[162:163], v[162:163], s[26:27], v[126:127] op_sel_hi:[1,0,0]
	v_pk_fma_f32 v[194:195], v[194:195], s[26:27], v[126:127] op_sel_hi:[1,0,0]
	v_max_f32_e32 v161, 0x4b000001, v163
	v_max_f32_e32 v162, 0x4b000001, v162
	v_pk_fma_f32 v[118:119], v[118:119], s[26:27], v[126:127] op_sel_hi:[1,0,0]
	v_perm_b32 v161, v161, v162, s58
	v_max_f32_e32 v162, 0x4b000001, v195
	v_max_f32_e32 v163, 0x4b000001, v194
	v_pk_fma_f32 v[120:121], v[120:121], s[26:27], v[126:127] op_sel_hi:[1,0,0]
	v_max_f32_e32 v119, 0x4b000001, v119
	v_max_f32_e32 v118, 0x4b000001, v118
	v_perm_b32 v162, v162, v163, s58
	v_perm_b32 v118, v119, v118, s58
	v_max_f32_e32 v119, 0x4b000001, v121
	v_max_f32_e32 v120, 0x4b000001, v120
	v_lshl_or_b32 v163, v115, 16, v114
	v_perm_b32 v160, v199, v200, s58
	v_perm_b32 v119, v119, v120, s58
	v_lshl_or_b32 v160, v160, 16, v198
	v_lshl_or_b32 v161, v162, 16, v161
	v_lshl_or_b32 v162, v119, 16, v118
	global_store_dwordx4 v[216:217], v[160:163], off
	v_pk_mul_f32 v[98:99], v[130:131], v[98:99]
	v_pk_mul_f32 v[110:111], v[174:175], v[110:111]
	v_pk_mul_f32 v[100:101], v[132:133], v[100:101]
	v_pk_fma_f32 v[98:99], v[98:99], v[188:189], v[128:129] op_sel_hi:[1,0,1]
	v_pk_fma_f32 v[110:111], v[110:111], v[188:189], v[172:173] op_sel_hi:[1,0,1]
	v_pk_fma_f32 v[100:101], v[100:101], v[188:189], v[124:125] op_sel_hi:[1,0,1]
	v_exp_f32_e32 v98, v98
	v_exp_f32_e32 v99, v99
	v_exp_f32_e32 v110, v110
;     __device__ __forceinline__ void operator()(const f32x4 (&acc)[2][2][4][2], const Unit& u, int wr, int wc, int fr, int fq) const {
;     ...
; #pragma unroll
;         for (int ai = 0; ai < 2; ++ai)
; #pragma unroll
;             for (int m = 0; m < 4; ++m) { unsigned char* rowp = O + (size_t)(row0 + ai * HALF + m * 16) * 8704 + gbase + (col0 & 1023);
;                 const float rs = rsv[ai * 4 + m];
;                 u32x4 w; EPG_Q4(w.x, acc[ai][0][m][0], wv[0][0], rs, bv[0][0]); EPG_Q4(w.y, acc[ai][0][m][1], wv[0][1], rs, bv[0][1]);
;                 EPG_Q4(w.z, acc[ai][1][m][0], wv[1][0], rs, bv[1][0]); EPG_Q4(w.w, acc[ai][1][m][1], wv[1][1], rs, bv[1][1]);
;                 *(u32x4*)rowp = w; }
	v_exp_f32_e32 v111, v111
	v_exp_f32_e32 v100, v100
	v_exp_f32_e32 v101, v101
	v_pk_mul_f32 v[108:109], v[168:169], v[108:109]
	v_pk_mul_f32 v[102:103], v[138:139], v[102:103]
	v_pk_add_f32 v[98:99], v[98:99], 1.0 op_sel_hi:[1,0]
	v_pk_mul_f32 v[112:113], v[176:177], v[112:113]
	v_pk_add_f32 v[110:111], v[110:111], 1.0 op_sel_hi:[1,0]
	v_pk_mul_f32 v[106:107], v[166:167], v[106:107]
	v_pk_fma_f32 v[108:109], v[108:109], v[188:189], v[144:145] op_sel_hi:[1,0,1]
	v_pk_mul_f32 v[104:105], v[140:141], v[104:105]
	v_pk_fma_f32 v[102:103], v[102:103], v[188:189], v[136:137] op_sel_hi:[1,0,1]
	v_pk_add_f32 v[100:101], v[100:101], 1.0 op_sel_hi:[1,0]
	v_rcp_f32_e32 v98, v98
	v_rcp_f32_e32 v99, v99
	v_pk_fma_f32 v[112:113], v[112:113], v[188:189], v[170:171] op_sel_hi:[1,0,1]
	v_rcp_f32_e32 v110, v110
	v_rcp_f32_e32 v111, v111
	v_pk_fma_f32 v[106:107], v[106:107], v[188:189], v[164:165] op_sel_hi:[1,0,1]
	v_exp_f32_e32 v108, v108
	v_exp_f32_e32 v109, v109
	v_pk_fma_f32 v[104:105], v[104:105], v[188:189], v[134:135] op_sel_hi:[1,0,1]
	v_exp_f32_e32 v102, v102
	v_exp_f32_e32 v103, v103
	v_rcp_f32_e32 v100, v100
	v_rcp_f32_e32 v101, v101
	v_exp_f32_e32 v112, v112
	v_exp_f32_e32 v113, v113
	v_exp_f32_e32 v106, v106
	v_exp_f32_e32 v107, v107
	v_exp_f32_e32 v104, v104
	v_exp_f32_e32 v105, v105
	v_pk_fma_f32 v[98:99], v[98:99], s[26:27], v[126:127] op_sel_hi:[1,0,0]
	v_pk_fma_f32 v[110:111], v[110:111], s[26:27], v[126:127] op_sel_hi:[1,0,0]
	v_pk_add_f32 v[108:109], v[108:109], 1.0 op_sel_hi:[1,0]
	v_pk_add_f32 v[102:103], v[102:103], 1.0 op_sel_hi:[1,0]
	v_pk_fma_f32 v[100:101], v[100:101], s[26:27], v[126:127] op_sel_hi:[1,0,0]
	v_max_f32_e32 v99, 0x4b000001, v99
	v_max_f32_e32 v98, 0x4b000001, v98
	v_pk_add_f32 v[112:113], v[112:113], 1.0 op_sel_hi:[1,0]
	v_max_f32_e32 v111, 0x4b000001, v111
	v_max_f32_e32 v110, 0x4b000001, v110
	v_pk_add_f32 v[106:107], v[106:107], 1.0 op_sel_hi:[1,0]
	v_rcp_f32_e32 v108, v108
	v_rcp_f32_e32 v109, v109
	v_pk_add_f32 v[104:105], v[104:105], 1.0 op_sel_hi:[1,0]
	v_rcp_f32_e32 v102, v102
	v_rcp_f32_e32 v103, v103
	v_perm_b32 v98, v99, v98, s58
	v_max_f32_e32 v99, 0x4b000001, v101
	v_max_f32_e32 v100, 0x4b000001, v100
	v_rcp_f32_e32 v112, v112
	v_rcp_f32_e32 v113, v113
	v_perm_b32 v116, v111, v110, s58
	v_rcp_f32_e32 v110, v106
	v_rcp_f32_e32 v111, v107
	v_rcp_f32_e32 v104, v104
	v_rcp_f32_e32 v105, v105
	v_perm_b32 v99, v99, v100, s58
	v_pk_fma_f32 v[108:109], v[108:109], s[26:27], v[126:127] op_sel_hi:[1,0,0]
	v_pk_fma_f32 v[102:103], v[102:103], s[26:27], v[126:127] op_sel_hi:[1,0,0]
	v_pk_fma_f32 v[112:113], v[112:113], s[26:27], v[126:127] op_sel_hi:[1,0,0]
	v_pk_fma_f32 v[110:111], v[110:111], s[26:27], v[126:127] op_sel_hi:[1,0,0]
	v_max_f32_e32 v109, 0x4b000001, v109
	v_max_f32_e32 v108, 0x4b000001, v108
	v_pk_fma_f32 v[104:105], v[104:105], s[26:27], v[126:127] op_sel_hi:[1,0,0]
	v_max_f32_e32 v103, 0x4b000001, v103
	v_max_f32_e32 v102, 0x4b000001, v102
	v_mad_i64_i32 v[114:115], s[2:3], v193, s57, v[142:143]
	v_max_f32_e32 v113, 0x4b000001, v113
	v_max_f32_e32 v112, 0x4b000001, v112
	v_max_f32_e32 v107, 0x4b000001, v111
	v_max_f32_e32 v110, 0x4b000001, v110
	v_perm_b32 v108, v109, v108, s58
	v_perm_b32 v102, v103, v102, s58
	v_max_f32_e32 v103, 0x4b000001, v105
	v_max_f32_e32 v104, 0x4b000001, v104
	v_lshl_or_b32 v109, v99, 16, v98
	v_lshl_add_u64 v[114:115], v[114:115], 0, s[0:1]
	v_perm_b32 v106, v113, v112, s58
	v_perm_b32 v107, v107, v110, s58
	v_perm_b32 v103, v103, v104, s58
	v_lshl_add_u64 v[114:115], v[114:115], 0, v[154:155]
	v_lshl_or_b32 v106, v106, 16, v116
	v_lshl_or_b32 v107, v108, 16, v107
	v_lshl_or_b32 v108, v103, 16, v102
	global_store_dwordx4 v[114:115], v[106:109], off
	v_pk_mul_f32 v[82:83], v[130:131], v[82:83]
	v_pk_mul_f32 v[94:95], v[174:175], v[94:95]
	v_pk_mul_f32 v[84:85], v[132:133], v[84:85]
	v_pk_fma_f32 v[82:83], v[82:83], v[186:187], v[128:129] op_sel_hi:[1,0,1]
	v_pk_fma_f32 v[94:95], v[94:95], v[186:187], v[172:173] op_sel_hi:[1,0,1]
	v_pk_fma_f32 v[84:85], v[84:85], v[186:187], v[124:125] op_sel_hi:[1,0,1]
	v_exp_f32_e32 v82, v82
	v_exp_f32_e32 v83, v83
	v_exp_f32_e32 v94, v94
	v_exp_f32_e32 v95, v95
	v_exp_f32_e32 v84, v84
	v_exp_f32_e32 v85, v85
	v_pk_mul_f32 v[92:93], v[168:169], v[92:93]
	v_pk_mul_f32 v[86:87], v[138:139], v[86:87]
	v_pk_add_f32 v[82:83], v[82:83], 1.0 op_sel_hi:[1,0]
	v_pk_mul_f32 v[96:97], v[176:177], v[96:97]
	v_pk_add_f32 v[94:95], v[94:95], 1.0 op_sel_hi:[1,0]
	v_pk_mul_f32 v[90:91], v[166:167], v[90:91]
	v_pk_fma_f32 v[92:93], v[92:93], v[186:187], v[144:145] op_sel_hi:[1,0,1]
	v_pk_mul_f32 v[88:89], v[140:141], v[88:89]
	v_pk_fma_f32 v[86:87], v[86:87], v[186:187], v[136:137] op_sel_hi:[1,0,1]
	v_pk_add_f32 v[84:85], v[84:85], 1.0 op_sel_hi:[1,0]
	v_rcp_f32_e32 v82, v82
	v_rcp_f32_e32 v83, v83
	v_pk_fma_f32 v[96:97], v[96:97], v[186:187], v[170:171] op_sel_hi:[1,0,1]
	v_rcp_f32_e32 v94, v94
	v_rcp_f32_e32 v95, v95
	v_pk_fma_f32 v[90:91], v[90:91], v[186:187], v[164:165] op_sel_hi:[1,0,1]
	v_exp_f32_e32 v92, v92
	v_exp_f32_e32 v93, v93
	v_pk_fma_f32 v[88:89], v[88:89], v[186:187], v[134:135] op_sel_hi:[1,0,1]
	v_exp_f32_e32 v86, v86
	v_exp_f32_e32 v87, v87
	v_rcp_f32_e32 v84, v84
	v_rcp_f32_e32 v85, v85
	v_exp_f32_e32 v96, v96
	v_exp_f32_e32 v97, v97
	v_exp_f32_e32 v90, v90
	v_exp_f32_e32 v91, v91
	v_exp_f32_e32 v88, v88
	v_exp_f32_e32 v89, v89
	v_pk_fma_f32 v[82:83], v[82:83], s[26:27], v[126:127] op_sel_hi:[1,0,0]
	v_pk_fma_f32 v[94:95], v[94:95], s[26:27], v[126:127] op_sel_hi:[1,0,0]
	v_pk_add_f32 v[92:93], v[92:93], 1.0 op_sel_hi:[1,0]
	v_pk_add_f32 v[86:87], v[86:87], 1.0 op_sel_hi:[1,0]
	v_pk_fma_f32 v[84:85], v[84:85], s[26:27], v[126:127] op_sel_hi:[1,0,0]
;     __device__ __forceinline__ void operator()(const f32x4 (&acc)[2][2][4][2], const Unit& u, int wr, int wc, int fr, int fq) const {
;     ...
; #pragma unroll
;         for (int ai = 0; ai < 2; ++ai)
; #pragma unroll
;             for (int m = 0; m < 4; ++m) { unsigned char* rowp = O + (size_t)(row0 + ai * HALF + m * 16) * 8704 + gbase + (col0 & 1023);
;                 const float rs = rsv[ai * 4 + m];
;                 u32x4 w; EPG_Q4(w.x, acc[ai][0][m][0], wv[0][0], rs, bv[0][0]); EPG_Q4(w.y, acc[ai][0][m][1], wv[0][1], rs, bv[0][1]);
;                 EPG_Q4(w.z, acc[ai][1][m][0], wv[1][0], rs, bv[1][0]); EPG_Q4(w.w, acc[ai][1][m][1], wv[1][1], rs, bv[1][1]);
;                 *(u32x4*)rowp = w; }
	v_max_f32_e32 v83, 0x4b000001, v83
	v_max_f32_e32 v82, 0x4b000001, v82
	v_pk_add_f32 v[96:97], v[96:97], 1.0 op_sel_hi:[1,0]
	v_max_f32_e32 v95, 0x4b000001, v95
	v_max_f32_e32 v94, 0x4b000001, v94
	v_pk_add_f32 v[90:91], v[90:91], 1.0 op_sel_hi:[1,0]
	v_rcp_f32_e32 v92, v92
	v_rcp_f32_e32 v93, v93
	v_pk_add_f32 v[88:89], v[88:89], 1.0 op_sel_hi:[1,0]
	v_rcp_f32_e32 v86, v86
	v_rcp_f32_e32 v87, v87
	v_perm_b32 v82, v83, v82, s58
	v_max_f32_e32 v83, 0x4b000001, v85
	v_max_f32_e32 v84, 0x4b000001, v84
	v_rcp_f32_e32 v96, v96
	v_rcp_f32_e32 v97, v97
	v_perm_b32 v100, v95, v94, s58
	v_rcp_f32_e32 v94, v90
	v_rcp_f32_e32 v95, v91
	v_rcp_f32_e32 v88, v88
	v_rcp_f32_e32 v89, v89
	v_perm_b32 v83, v83, v84, s58
	v_pk_fma_f32 v[92:93], v[92:93], s[26:27], v[126:127] op_sel_hi:[1,0,0]
	v_pk_fma_f32 v[86:87], v[86:87], s[26:27], v[126:127] op_sel_hi:[1,0,0]
	v_pk_fma_f32 v[96:97], v[96:97], s[26:27], v[126:127] op_sel_hi:[1,0,0]
	v_pk_fma_f32 v[94:95], v[94:95], s[26:27], v[126:127] op_sel_hi:[1,0,0]
	v_max_f32_e32 v93, 0x4b000001, v93
	v_max_f32_e32 v92, 0x4b000001, v92
	v_pk_fma_f32 v[88:89], v[88:89], s[26:27], v[126:127] op_sel_hi:[1,0,0]
	v_max_f32_e32 v87, 0x4b000001, v87
	v_max_f32_e32 v86, 0x4b000001, v86
	v_mad_i64_i32 v[98:99], s[2:3], v207, s57, v[142:143]
	v_max_f32_e32 v97, 0x4b000001, v97
	v_max_f32_e32 v96, 0x4b000001, v96
	v_max_f32_e32 v91, 0x4b000001, v95
	v_max_f32_e32 v94, 0x4b000001, v94
	v_perm_b32 v92, v93, v92, s58
	v_perm_b32 v86, v87, v86, s58
	v_max_f32_e32 v87, 0x4b000001, v89
	v_max_f32_e32 v88, 0x4b000001, v88
	v_lshl_or_b32 v93, v83, 16, v82
	v_lshl_add_u64 v[98:99], v[98:99], 0, s[0:1]
	v_perm_b32 v90, v97, v96, s58
	v_perm_b32 v91, v91, v94, s58
	v_perm_b32 v87, v87, v88, s58
	v_lshl_add_u64 v[98:99], v[98:99], 0, v[154:155]
	v_lshl_or_b32 v90, v90, 16, v100
	v_lshl_or_b32 v91, v92, 16, v91
	v_lshl_or_b32 v92, v87, 16, v86
	global_store_dwordx4 v[98:99], v[90:93], off
	v_pk_mul_f32 v[66:67], v[130:131], v[66:67]
	v_pk_mul_f32 v[78:79], v[174:175], v[78:79]
	v_pk_mul_f32 v[68:69], v[132:133], v[68:69]
	v_pk_fma_f32 v[66:67], v[66:67], v[184:185], v[128:129] op_sel_hi:[1,0,1]
	v_pk_fma_f32 v[78:79], v[78:79], v[184:185], v[172:173] op_sel_hi:[1,0,1]
	v_pk_fma_f32 v[68:69], v[68:69], v[184:185], v[124:125] op_sel_hi:[1,0,1]
	v_exp_f32_e32 v66, v66
	v_exp_f32_e32 v67, v67
	v_exp_f32_e32 v78, v78
	v_exp_f32_e32 v79, v79
	v_exp_f32_e32 v68, v68
	v_exp_f32_e32 v69, v69
	v_pk_mul_f32 v[76:77], v[168:169], v[76:77]
	v_pk_mul_f32 v[70:71], v[138:139], v[70:71]
	v_pk_add_f32 v[66:67], v[66:67], 1.0 op_sel_hi:[1,0]
	v_pk_mul_f32 v[80:81], v[176:177], v[80:81]
	v_pk_add_f32 v[78:79], v[78:79], 1.0 op_sel_hi:[1,0]
	v_pk_mul_f32 v[74:75], v[166:167], v[74:75]
	v_pk_fma_f32 v[76:77], v[76:77], v[184:185], v[144:145] op_sel_hi:[1,0,1]
	v_pk_mul_f32 v[72:73], v[140:141], v[72:73]
	v_pk_fma_f32 v[70:71], v[70:71], v[184:185], v[136:137] op_sel_hi:[1,0,1]
	v_pk_add_f32 v[68:69], v[68:69], 1.0 op_sel_hi:[1,0]
	v_rcp_f32_e32 v66, v66
	v_rcp_f32_e32 v67, v67
	v_pk_fma_f32 v[80:81], v[80:81], v[184:185], v[170:171] op_sel_hi:[1,0,1]
	v_rcp_f32_e32 v78, v78
	v_rcp_f32_e32 v79, v79
	v_pk_fma_f32 v[74:75], v[74:75], v[184:185], v[164:165] op_sel_hi:[1,0,1]
	v_exp_f32_e32 v76, v76
	v_exp_f32_e32 v77, v77
	v_pk_fma_f32 v[72:73], v[72:73], v[184:185], v[134:135] op_sel_hi:[1,0,1]
	v_exp_f32_e32 v70, v70
	v_exp_f32_e32 v71, v71
	v_rcp_f32_e32 v68, v68
	v_rcp_f32_e32 v69, v69
	v_exp_f32_e32 v80, v80
	v_exp_f32_e32 v81, v81
	v_exp_f32_e32 v74, v74
	v_exp_f32_e32 v75, v75
	v_exp_f32_e32 v72, v72
	v_exp_f32_e32 v73, v73
	v_pk_fma_f32 v[66:67], v[66:67], s[26:27], v[126:127] op_sel_hi:[1,0,0]
	v_pk_fma_f32 v[78:79], v[78:79], s[26:27], v[126:127] op_sel_hi:[1,0,0]
	v_pk_add_f32 v[76:77], v[76:77], 1.0 op_sel_hi:[1,0]
	v_pk_add_f32 v[70:71], v[70:71], 1.0 op_sel_hi:[1,0]
	v_pk_fma_f32 v[68:69], v[68:69], s[26:27], v[126:127] op_sel_hi:[1,0,0]
	v_max_f32_e32 v67, 0x4b000001, v67
	v_max_f32_e32 v66, 0x4b000001, v66
	v_pk_add_f32 v[80:81], v[80:81], 1.0 op_sel_hi:[1,0]
	v_max_f32_e32 v79, 0x4b000001, v79
	v_max_f32_e32 v78, 0x4b000001, v78
	v_pk_add_f32 v[74:75], v[74:75], 1.0 op_sel_hi:[1,0]
	v_rcp_f32_e32 v76, v76
	v_rcp_f32_e32 v77, v77
	v_pk_add_f32 v[72:73], v[72:73], 1.0 op_sel_hi:[1,0]
	v_rcp_f32_e32 v70, v70
	v_rcp_f32_e32 v71, v71
	v_perm_b32 v66, v67, v66, s58
	v_max_f32_e32 v67, 0x4b000001, v69
	v_max_f32_e32 v68, 0x4b000001, v68
	v_rcp_f32_e32 v80, v80
	v_rcp_f32_e32 v81, v81
	v_perm_b32 v84, v79, v78, s58
	v_rcp_f32_e32 v78, v74
	v_rcp_f32_e32 v79, v75
	v_rcp_f32_e32 v72, v72
	v_rcp_f32_e32 v73, v73
	v_perm_b32 v67, v67, v68, s58
	v_pk_fma_f32 v[76:77], v[76:77], s[26:27], v[126:127] op_sel_hi:[1,0,0]
	v_pk_fma_f32 v[70:71], v[70:71], s[26:27], v[126:127] op_sel_hi:[1,0,0]
	v_pk_fma_f32 v[80:81], v[80:81], s[26:27], v[126:127] op_sel_hi:[1,0,0]
	v_pk_fma_f32 v[78:79], v[78:79], s[26:27], v[126:127] op_sel_hi:[1,0,0]
	v_max_f32_e32 v77, 0x4b000001, v77
	v_max_f32_e32 v76, 0x4b000001, v76
	v_pk_fma_f32 v[72:73], v[72:73], s[26:27], v[126:127] op_sel_hi:[1,0,0]
	v_max_f32_e32 v71, 0x4b000001, v71
	v_max_f32_e32 v70, 0x4b000001, v70
	v_mad_i64_i32 v[82:83], s[2:3], v192, s57, v[142:143]
	v_max_f32_e32 v81, 0x4b000001, v81
	v_max_f32_e32 v80, 0x4b000001, v80
	v_max_f32_e32 v75, 0x4b000001, v79
	v_max_f32_e32 v78, 0x4b000001, v78
	v_perm_b32 v76, v77, v76, s58
	v_perm_b32 v70, v71, v70, s58
	v_max_f32_e32 v71, 0x4b000001, v73
	v_max_f32_e32 v72, 0x4b000001, v72
	v_lshl_or_b32 v77, v67, 16, v66
	v_lshl_add_u64 v[82:83], v[82:83], 0, s[0:1]
	v_perm_b32 v74, v81, v80, s58
	v_perm_b32 v75, v75, v78, s58
	v_perm_b32 v71, v71, v72, s58
;     __device__ __forceinline__ void operator()(const f32x4 (&acc)[2][2][4][2], const Unit& u, int wr, int wc, int fr, int fq) const {
;     ...
; #pragma unroll
;         for (int ai = 0; ai < 2; ++ai)
; #pragma unroll
;             for (int m = 0; m < 4; ++m) { unsigned char* rowp = O + (size_t)(row0 + ai * HALF + m * 16) * 8704 + gbase + (col0 & 1023);
;                 const float rs = rsv[ai * 4 + m];
;                 u32x4 w; EPG_Q4(w.x, acc[ai][0][m][0], wv[0][0], rs, bv[0][0]); EPG_Q4(w.y, acc[ai][0][m][1], wv[0][1], rs, bv[0][1]);
;                 EPG_Q4(w.z, acc[ai][1][m][0], wv[1][0], rs, bv[1][0]); EPG_Q4(w.w, acc[ai][1][m][1], wv[1][1], rs, bv[1][1]);
;                 *(u32x4*)rowp = w; }
	v_lshl_add_u64 v[82:83], v[82:83], 0, v[154:155]
	v_lshl_or_b32 v74, v74, 16, v84
	v_lshl_or_b32 v75, v76, 16, v75
	v_lshl_or_b32 v76, v71, 16, v70
	global_store_dwordx4 v[82:83], v[74:77], off
	v_pk_mul_f32 v[50:51], v[130:131], v[50:51]
	v_pk_mul_f32 v[62:63], v[174:175], v[62:63]
	v_pk_mul_f32 v[52:53], v[132:133], v[52:53]
	v_pk_fma_f32 v[50:51], v[50:51], v[182:183], v[128:129] op_sel_hi:[1,0,1]
	v_pk_fma_f32 v[62:63], v[62:63], v[182:183], v[172:173] op_sel_hi:[1,0,1]
	v_pk_fma_f32 v[52:53], v[52:53], v[182:183], v[124:125] op_sel_hi:[1,0,1]
	v_exp_f32_e32 v50, v50
	v_exp_f32_e32 v51, v51
	v_exp_f32_e32 v62, v62
	v_exp_f32_e32 v63, v63
	v_exp_f32_e32 v52, v52
	v_exp_f32_e32 v53, v53
	v_pk_mul_f32 v[60:61], v[168:169], v[60:61]
	v_pk_mul_f32 v[54:55], v[138:139], v[54:55]
	v_pk_add_f32 v[50:51], v[50:51], 1.0 op_sel_hi:[1,0]
	v_pk_mul_f32 v[64:65], v[176:177], v[64:65]
	v_pk_add_f32 v[62:63], v[62:63], 1.0 op_sel_hi:[1,0]
	v_pk_mul_f32 v[58:59], v[166:167], v[58:59]
	v_pk_fma_f32 v[60:61], v[60:61], v[182:183], v[144:145] op_sel_hi:[1,0,1]
	v_pk_mul_f32 v[56:57], v[140:141], v[56:57]
	v_pk_fma_f32 v[54:55], v[54:55], v[182:183], v[136:137] op_sel_hi:[1,0,1]
	v_pk_add_f32 v[52:53], v[52:53], 1.0 op_sel_hi:[1,0]
	v_rcp_f32_e32 v50, v50
	v_rcp_f32_e32 v51, v51
	v_pk_fma_f32 v[64:65], v[64:65], v[182:183], v[170:171] op_sel_hi:[1,0,1]
	v_rcp_f32_e32 v62, v62
	v_rcp_f32_e32 v63, v63
	v_pk_fma_f32 v[58:59], v[58:59], v[182:183], v[164:165] op_sel_hi:[1,0,1]
	v_exp_f32_e32 v60, v60
	v_exp_f32_e32 v61, v61
	v_pk_fma_f32 v[56:57], v[56:57], v[182:183], v[134:135] op_sel_hi:[1,0,1]
	v_exp_f32_e32 v54, v54
	v_exp_f32_e32 v55, v55
	v_rcp_f32_e32 v52, v52
	v_rcp_f32_e32 v53, v53
	v_exp_f32_e32 v64, v64
	v_exp_f32_e32 v65, v65
	v_exp_f32_e32 v58, v58
	v_exp_f32_e32 v59, v59
	v_exp_f32_e32 v56, v56
	v_exp_f32_e32 v57, v57
	v_pk_fma_f32 v[50:51], v[50:51], s[26:27], v[126:127] op_sel_hi:[1,0,0]
	v_pk_fma_f32 v[62:63], v[62:63], s[26:27], v[126:127] op_sel_hi:[1,0,0]
	v_pk_add_f32 v[60:61], v[60:61], 1.0 op_sel_hi:[1,0]
	v_pk_add_f32 v[54:55], v[54:55], 1.0 op_sel_hi:[1,0]
	v_pk_fma_f32 v[52:53], v[52:53], s[26:27], v[126:127] op_sel_hi:[1,0,0]
	v_max_f32_e32 v51, 0x4b000001, v51
	v_max_f32_e32 v50, 0x4b000001, v50
	v_pk_add_f32 v[64:65], v[64:65], 1.0 op_sel_hi:[1,0]
	v_max_f32_e32 v63, 0x4b000001, v63
	v_max_f32_e32 v62, 0x4b000001, v62
	v_pk_add_f32 v[58:59], v[58:59], 1.0 op_sel_hi:[1,0]
	v_rcp_f32_e32 v60, v60
	v_rcp_f32_e32 v61, v61
	v_pk_add_f32 v[56:57], v[56:57], 1.0 op_sel_hi:[1,0]
	v_rcp_f32_e32 v54, v54
	v_rcp_f32_e32 v55, v55
	v_perm_b32 v50, v51, v50, s58
	v_max_f32_e32 v51, 0x4b000001, v53
	v_max_f32_e32 v52, 0x4b000001, v52
	v_rcp_f32_e32 v64, v64
	v_rcp_f32_e32 v65, v65
	v_perm_b32 v68, v63, v62, s58
	v_rcp_f32_e32 v62, v58
	v_rcp_f32_e32 v63, v59
	v_rcp_f32_e32 v56, v56
	v_rcp_f32_e32 v57, v57
	v_perm_b32 v51, v51, v52, s58
	v_pk_fma_f32 v[60:61], v[60:61], s[26:27], v[126:127] op_sel_hi:[1,0,0]
	v_pk_fma_f32 v[54:55], v[54:55], s[26:27], v[126:127] op_sel_hi:[1,0,0]
	v_pk_fma_f32 v[64:65], v[64:65], s[26:27], v[126:127] op_sel_hi:[1,0,0]
	v_pk_fma_f32 v[62:63], v[62:63], s[26:27], v[126:127] op_sel_hi:[1,0,0]
	v_max_f32_e32 v61, 0x4b000001, v61
	v_max_f32_e32 v60, 0x4b000001, v60
	v_pk_fma_f32 v[56:57], v[56:57], s[26:27], v[126:127] op_sel_hi:[1,0,0]
	v_max_f32_e32 v55, 0x4b000001, v55
	v_max_f32_e32 v54, 0x4b000001, v54
	v_mad_i64_i32 v[66:67], s[2:3], v191, s57, v[142:143]
	v_max_f32_e32 v65, 0x4b000001, v65
	v_max_f32_e32 v64, 0x4b000001, v64
	v_max_f32_e32 v59, 0x4b000001, v63
	v_max_f32_e32 v62, 0x4b000001, v62
	v_perm_b32 v60, v61, v60, s58
	v_perm_b32 v54, v55, v54, s58
	v_max_f32_e32 v55, 0x4b000001, v57
	v_max_f32_e32 v56, 0x4b000001, v56
	v_lshl_or_b32 v61, v51, 16, v50
	v_lshl_add_u64 v[66:67], v[66:67], 0, s[0:1]
	v_perm_b32 v58, v65, v64, s58
	v_perm_b32 v59, v59, v62, s58
	v_perm_b32 v55, v55, v56, s58
	v_lshl_add_u64 v[66:67], v[66:67], 0, v[154:155]
	v_lshl_or_b32 v58, v58, 16, v68
	v_lshl_or_b32 v59, v60, 16, v59
	v_lshl_or_b32 v60, v55, 16, v54
	global_store_dwordx4 v[66:67], v[58:61], off
	v_pk_mul_f32 v[34:35], v[130:131], v[34:35]
	v_pk_mul_f32 v[46:47], v[174:175], v[46:47]
	v_pk_mul_f32 v[36:37], v[132:133], v[36:37]
	v_pk_fma_f32 v[34:35], v[34:35], v[180:181], v[128:129] op_sel_hi:[1,0,1]
	v_pk_fma_f32 v[46:47], v[46:47], v[180:181], v[172:173] op_sel_hi:[1,0,1]
	v_pk_fma_f32 v[36:37], v[36:37], v[180:181], v[124:125] op_sel_hi:[1,0,1]
	v_exp_f32_e32 v34, v34
	v_exp_f32_e32 v35, v35
	v_exp_f32_e32 v46, v46
	v_exp_f32_e32 v47, v47
	v_exp_f32_e32 v36, v36
	v_exp_f32_e32 v37, v37
	v_pk_mul_f32 v[44:45], v[168:169], v[44:45]
	v_pk_mul_f32 v[38:39], v[138:139], v[38:39]
	v_pk_add_f32 v[34:35], v[34:35], 1.0 op_sel_hi:[1,0]
	v_pk_mul_f32 v[48:49], v[176:177], v[48:49]
	v_pk_add_f32 v[46:47], v[46:47], 1.0 op_sel_hi:[1,0]
	v_pk_mul_f32 v[42:43], v[166:167], v[42:43]
	v_pk_fma_f32 v[44:45], v[44:45], v[180:181], v[144:145] op_sel_hi:[1,0,1]
	v_pk_mul_f32 v[40:41], v[140:141], v[40:41]
	v_pk_fma_f32 v[38:39], v[38:39], v[180:181], v[136:137] op_sel_hi:[1,0,1]
	v_pk_add_f32 v[36:37], v[36:37], 1.0 op_sel_hi:[1,0]
	v_rcp_f32_e32 v34, v34
	v_rcp_f32_e32 v35, v35
	v_pk_fma_f32 v[48:49], v[48:49], v[180:181], v[170:171] op_sel_hi:[1,0,1]
	v_rcp_f32_e32 v46, v46
	v_rcp_f32_e32 v47, v47
	v_pk_fma_f32 v[42:43], v[42:43], v[180:181], v[164:165] op_sel_hi:[1,0,1]
	v_exp_f32_e32 v44, v44
	v_exp_f32_e32 v45, v45
	v_pk_fma_f32 v[40:41], v[40:41], v[180:181], v[134:135] op_sel_hi:[1,0,1]
	v_exp_f32_e32 v38, v38
	v_exp_f32_e32 v39, v39
	v_rcp_f32_e32 v36, v36
	v_rcp_f32_e32 v37, v37
	v_exp_f32_e32 v48, v48
	v_exp_f32_e32 v49, v49
;     __device__ __forceinline__ void operator()(const f32x4 (&acc)[2][2][4][2], const Unit& u, int wr, int wc, int fr, int fq) const {
;     ...
; #pragma unroll
;         for (int ai = 0; ai < 2; ++ai)
; #pragma unroll
;             for (int m = 0; m < 4; ++m) { unsigned char* rowp = O + (size_t)(row0 + ai * HALF + m * 16) * 8704 + gbase + (col0 & 1023);
;                 const float rs = rsv[ai * 4 + m];
;                 u32x4 w; EPG_Q4(w.x, acc[ai][0][m][0], wv[0][0], rs, bv[0][0]); EPG_Q4(w.y, acc[ai][0][m][1], wv[0][1], rs, bv[0][1]);
;                 EPG_Q4(w.z, acc[ai][1][m][0], wv[1][0], rs, bv[1][0]); EPG_Q4(w.w, acc[ai][1][m][1], wv[1][1], rs, bv[1][1]);
;                 *(u32x4*)rowp = w; }
	v_exp_f32_e32 v42, v42
	v_exp_f32_e32 v43, v43
	v_exp_f32_e32 v40, v40
	v_exp_f32_e32 v41, v41
	v_pk_fma_f32 v[34:35], v[34:35], s[26:27], v[126:127] op_sel_hi:[1,0,0]
	v_pk_fma_f32 v[46:47], v[46:47], s[26:27], v[126:127] op_sel_hi:[1,0,0]
	v_pk_add_f32 v[44:45], v[44:45], 1.0 op_sel_hi:[1,0]
	v_pk_add_f32 v[38:39], v[38:39], 1.0 op_sel_hi:[1,0]
	v_pk_fma_f32 v[36:37], v[36:37], s[26:27], v[126:127] op_sel_hi:[1,0,0]
	v_max_f32_e32 v35, 0x4b000001, v35
	v_max_f32_e32 v34, 0x4b000001, v34
	v_pk_add_f32 v[48:49], v[48:49], 1.0 op_sel_hi:[1,0]
	v_max_f32_e32 v47, 0x4b000001, v47
	v_max_f32_e32 v46, 0x4b000001, v46
	v_pk_add_f32 v[42:43], v[42:43], 1.0 op_sel_hi:[1,0]
	v_rcp_f32_e32 v44, v44
	v_rcp_f32_e32 v45, v45
	v_pk_add_f32 v[40:41], v[40:41], 1.0 op_sel_hi:[1,0]
	v_rcp_f32_e32 v38, v38
	v_rcp_f32_e32 v39, v39
	v_perm_b32 v34, v35, v34, s58
	v_max_f32_e32 v35, 0x4b000001, v37
	v_max_f32_e32 v36, 0x4b000001, v36
	v_rcp_f32_e32 v48, v48
	v_rcp_f32_e32 v49, v49
	v_perm_b32 v52, v47, v46, s58
	v_rcp_f32_e32 v46, v42
	v_rcp_f32_e32 v47, v43
	v_rcp_f32_e32 v40, v40
	v_rcp_f32_e32 v41, v41
	v_perm_b32 v35, v35, v36, s58
	v_pk_fma_f32 v[44:45], v[44:45], s[26:27], v[126:127] op_sel_hi:[1,0,0]
	v_pk_fma_f32 v[38:39], v[38:39], s[26:27], v[126:127] op_sel_hi:[1,0,0]
	v_pk_fma_f32 v[48:49], v[48:49], s[26:27], v[126:127] op_sel_hi:[1,0,0]
	v_pk_fma_f32 v[46:47], v[46:47], s[26:27], v[126:127] op_sel_hi:[1,0,0]
	v_max_f32_e32 v45, 0x4b000001, v45
	v_max_f32_e32 v44, 0x4b000001, v44
	v_pk_fma_f32 v[40:41], v[40:41], s[26:27], v[126:127] op_sel_hi:[1,0,0]
	v_max_f32_e32 v39, 0x4b000001, v39
	v_max_f32_e32 v38, 0x4b000001, v38
	v_mad_i64_i32 v[50:51], s[2:3], v190, s57, v[142:143]
	v_max_f32_e32 v49, 0x4b000001, v49
	v_max_f32_e32 v48, 0x4b000001, v48
	v_max_f32_e32 v43, 0x4b000001, v47
	v_max_f32_e32 v46, 0x4b000001, v46
	v_perm_b32 v44, v45, v44, s58
	v_perm_b32 v38, v39, v38, s58
	v_max_f32_e32 v39, 0x4b000001, v41
	v_max_f32_e32 v40, 0x4b000001, v40
	v_lshl_or_b32 v45, v35, 16, v34
	v_lshl_add_u64 v[50:51], v[50:51], 0, s[0:1]
	v_perm_b32 v42, v49, v48, s58
	v_perm_b32 v43, v43, v46, s58
	v_perm_b32 v39, v39, v40, s58
	v_lshl_add_u64 v[50:51], v[50:51], 0, v[154:155]
	v_lshl_or_b32 v42, v42, 16, v52
	v_lshl_or_b32 v43, v44, 16, v43
	v_lshl_or_b32 v44, v39, 16, v38
	global_store_dwordx4 v[50:51], v[42:45], off
	v_pk_mul_f32 v[18:19], v[130:131], v[18:19]
	v_pk_mul_f32 v[30:31], v[174:175], v[30:31]
	v_pk_mul_f32 v[20:21], v[132:133], v[20:21]
	v_pk_fma_f32 v[18:19], v[18:19], v[178:179], v[128:129] op_sel_hi:[1,0,1]
	v_pk_fma_f32 v[30:31], v[30:31], v[178:179], v[172:173] op_sel_hi:[1,0,1]
	v_pk_fma_f32 v[20:21], v[20:21], v[178:179], v[124:125] op_sel_hi:[1,0,1]
	v_exp_f32_e32 v18, v18
	v_exp_f32_e32 v19, v19
	v_exp_f32_e32 v30, v30
	v_exp_f32_e32 v31, v31
	v_exp_f32_e32 v20, v20
	v_exp_f32_e32 v21, v21
	v_pk_mul_f32 v[28:29], v[168:169], v[28:29]
	v_pk_mul_f32 v[22:23], v[138:139], v[22:23]
	v_pk_add_f32 v[18:19], v[18:19], 1.0 op_sel_hi:[1,0]
	v_pk_mul_f32 v[32:33], v[176:177], v[32:33]
	v_pk_add_f32 v[30:31], v[30:31], 1.0 op_sel_hi:[1,0]
	v_pk_mul_f32 v[26:27], v[166:167], v[26:27]
	v_pk_fma_f32 v[28:29], v[28:29], v[178:179], v[144:145] op_sel_hi:[1,0,1]
	v_pk_mul_f32 v[24:25], v[140:141], v[24:25]
	v_pk_fma_f32 v[22:23], v[22:23], v[178:179], v[136:137] op_sel_hi:[1,0,1]
	v_pk_add_f32 v[20:21], v[20:21], 1.0 op_sel_hi:[1,0]
	v_rcp_f32_e32 v18, v18
	v_rcp_f32_e32 v19, v19
	v_pk_fma_f32 v[32:33], v[32:33], v[178:179], v[170:171] op_sel_hi:[1,0,1]
	v_rcp_f32_e32 v30, v30
	v_rcp_f32_e32 v31, v31
	v_pk_fma_f32 v[26:27], v[26:27], v[178:179], v[164:165] op_sel_hi:[1,0,1]
	v_exp_f32_e32 v28, v28
	v_exp_f32_e32 v29, v29
	v_pk_fma_f32 v[24:25], v[24:25], v[178:179], v[134:135] op_sel_hi:[1,0,1]
	v_exp_f32_e32 v22, v22
	v_exp_f32_e32 v23, v23
	v_rcp_f32_e32 v20, v20
	v_rcp_f32_e32 v21, v21
	v_exp_f32_e32 v32, v32
	v_exp_f32_e32 v33, v33
	v_exp_f32_e32 v26, v26
	v_exp_f32_e32 v27, v27
	v_exp_f32_e32 v24, v24
	v_exp_f32_e32 v25, v25
	v_pk_fma_f32 v[18:19], v[18:19], s[26:27], v[126:127] op_sel_hi:[1,0,0]
	v_pk_fma_f32 v[30:31], v[30:31], s[26:27], v[126:127] op_sel_hi:[1,0,0]
	v_pk_add_f32 v[28:29], v[28:29], 1.0 op_sel_hi:[1,0]
	v_pk_add_f32 v[22:23], v[22:23], 1.0 op_sel_hi:[1,0]
	v_pk_fma_f32 v[20:21], v[20:21], s[26:27], v[126:127] op_sel_hi:[1,0,0]
	v_max_f32_e32 v19, 0x4b000001, v19
	v_max_f32_e32 v18, 0x4b000001, v18
	v_pk_add_f32 v[32:33], v[32:33], 1.0 op_sel_hi:[1,0]
	v_max_f32_e32 v31, 0x4b000001, v31
	v_max_f32_e32 v30, 0x4b000001, v30
	v_pk_add_f32 v[26:27], v[26:27], 1.0 op_sel_hi:[1,0]
	v_rcp_f32_e32 v28, v28
	v_rcp_f32_e32 v29, v29
	v_pk_add_f32 v[24:25], v[24:25], 1.0 op_sel_hi:[1,0]
	v_rcp_f32_e32 v22, v22
	v_rcp_f32_e32 v23, v23
	v_perm_b32 v18, v19, v18, s58
	v_max_f32_e32 v19, 0x4b000001, v21
	v_max_f32_e32 v20, 0x4b000001, v20
	v_rcp_f32_e32 v32, v32
	v_rcp_f32_e32 v33, v33
	v_perm_b32 v36, v31, v30, s58
	v_rcp_f32_e32 v30, v26
	v_rcp_f32_e32 v31, v27
	v_rcp_f32_e32 v24, v24
	v_rcp_f32_e32 v25, v25
	v_perm_b32 v19, v19, v20, s58
	v_pk_fma_f32 v[28:29], v[28:29], s[26:27], v[126:127] op_sel_hi:[1,0,0]
; #define PG8_BAR __builtin_amdgcn_s_barrier()
;     __device__ __forceinline__ void operator()(const f32x4 (&acc)[2][2][4][2], const Unit& u, int wr, int wc, int fr, int fq) const {
;     ...
; #pragma unroll
;         for (int ai = 0; ai < 2; ++ai)
; #pragma unroll
;             for (int m = 0; m < 4; ++m) { unsigned char* rowp = O + (size_t)(row0 + ai * HALF + m * 16) * 8704 + gbase + (col0 & 1023);
;                 const float rs = rsv[ai * 4 + m];
;                 u32x4 w; EPG_Q4(w.x, acc[ai][0][m][0], wv[0][0], rs, bv[0][0]); EPG_Q4(w.y, acc[ai][0][m][1], wv[0][1], rs, bv[0][1]);
;                 EPG_Q4(w.z, acc[ai][1][m][0], wv[1][0], rs, bv[1][0]); EPG_Q4(w.w, acc[ai][1][m][1], wv[1][1], rs, bv[1][1]);
;                 *(u32x4*)rowp = w; }
; template <class Epi, class Sched, class Gemm, bool ALIGN_EPI = false, bool SP2 = false>
; __device__ __forceinline__ void gemm_phase(PG8_LAS unsigned char* lds, const Gemm g, const Sched& S, const Epi& E) {
;     ...
;         if (!has_next) break;
;         if constexpr (!epi_chain<Epi>::value) {
; #pragma unroll
;         for (int a = 0; a < 2; ++a)
; #pragma unroll
;             for (int b = 0; b < 2; ++b)
; #pragma unroll
;                 for (int m = 0; m < 4; ++m)
; #pragma unroll
;                     for (int n = 0; n < 2; ++n) acc[a][b][m][n] = (f32x4){0.f, 0.f, 0.f, 0.f};
;         }
;         cur = nxt; cA = nA; cB = nB; ++ui;
;         if constexpr (ALIGN_EPI) { if (wr == 1) PG8_BAR; }
	v_pk_fma_f32 v[22:23], v[22:23], s[26:27], v[126:127] op_sel_hi:[1,0,0]
	v_pk_fma_f32 v[32:33], v[32:33], s[26:27], v[126:127] op_sel_hi:[1,0,0]
	v_pk_fma_f32 v[30:31], v[30:31], s[26:27], v[126:127] op_sel_hi:[1,0,0]
	v_max_f32_e32 v29, 0x4b000001, v29
	v_max_f32_e32 v28, 0x4b000001, v28
	v_pk_fma_f32 v[24:25], v[24:25], s[26:27], v[126:127] op_sel_hi:[1,0,0]
	v_max_f32_e32 v23, 0x4b000001, v23
	v_max_f32_e32 v22, 0x4b000001, v22
	v_mad_i64_i32 v[34:35], s[2:3], v189, s57, v[142:143]
	v_max_f32_e32 v33, 0x4b000001, v33
	v_max_f32_e32 v32, 0x4b000001, v32
	v_max_f32_e32 v27, 0x4b000001, v31
	v_max_f32_e32 v30, 0x4b000001, v30
	v_perm_b32 v28, v29, v28, s58
	v_perm_b32 v22, v23, v22, s58
	v_max_f32_e32 v23, 0x4b000001, v25
	v_max_f32_e32 v24, 0x4b000001, v24
	v_lshl_or_b32 v29, v19, 16, v18
	v_lshl_add_u64 v[34:35], v[34:35], 0, s[0:1]
	v_perm_b32 v26, v33, v32, s58
	v_perm_b32 v27, v27, v30, s58
	v_perm_b32 v23, v23, v24, s58
	v_lshl_add_u64 v[34:35], v[34:35], 0, v[154:155]
	v_lshl_or_b32 v26, v26, 16, v36
	v_lshl_or_b32 v27, v28, 16, v27
	v_lshl_or_b32 v28, v23, 16, v22
	global_store_dwordx4 v[34:35], v[26:29], off
	v_pk_mul_f32 v[14:15], v[174:175], v[14:15]
	v_pk_fma_f32 v[14:15], v[14:15], v[122:123], v[172:173] op_sel_hi:[1,0,1]
	v_exp_f32_e32 v14, v14
	v_exp_f32_e32 v15, v15
	v_pk_mul_f32 v[6:7], v[138:139], v[6:7]
	v_pk_mul_f32 v[2:3], v[130:131], v[2:3]
	v_pk_mul_f32 v[16:17], v[176:177], v[16:17]
	v_pk_add_f32 v[14:15], v[14:15], 1.0 op_sel_hi:[1,0]
	v_pk_mul_f32 v[12:13], v[168:169], v[12:13]
	v_pk_mul_f32 v[10:11], v[166:167], v[10:11]
	v_pk_mul_f32 v[8:9], v[140:141], v[8:9]
	v_pk_fma_f32 v[6:7], v[6:7], v[122:123], v[136:137] op_sel_hi:[1,0,1]
	v_pk_mul_f32 v[4:5], v[132:133], v[4:5]
	v_pk_fma_f32 v[2:3], v[2:3], v[122:123], v[128:129] op_sel_hi:[1,0,1]
	v_pk_fma_f32 v[16:17], v[16:17], v[122:123], v[170:171] op_sel_hi:[1,0,1]
	v_rcp_f32_e32 v14, v14
	v_rcp_f32_e32 v15, v15
	v_pk_fma_f32 v[12:13], v[12:13], v[122:123], v[144:145] op_sel_hi:[1,0,1]
	v_pk_fma_f32 v[10:11], v[10:11], v[122:123], v[164:165] op_sel_hi:[1,0,1]
	v_pk_fma_f32 v[8:9], v[8:9], v[122:123], v[134:135] op_sel_hi:[1,0,1]
	v_exp_f32_e32 v6, v6
	v_exp_f32_e32 v7, v7
	v_pk_fma_f32 v[4:5], v[4:5], v[122:123], v[124:125] op_sel_hi:[1,0,1]
	v_exp_f32_e32 v2, v2
	v_exp_f32_e32 v3, v3
	v_exp_f32_e32 v16, v16
	v_exp_f32_e32 v17, v17
	v_exp_f32_e32 v10, v10
	v_exp_f32_e32 v12, v12
	v_exp_f32_e32 v13, v13
	v_exp_f32_e32 v11, v11
	v_exp_f32_e32 v8, v8
	v_exp_f32_e32 v9, v9
	v_exp_f32_e32 v4, v4
	v_exp_f32_e32 v5, v5
	v_pk_fma_f32 v[14:15], v[14:15], s[26:27], v[126:127] op_sel_hi:[1,0,0]
	v_pk_add_f32 v[6:7], v[6:7], 1.0 op_sel_hi:[1,0]
	v_pk_add_f32 v[2:3], v[2:3], 1.0 op_sel_hi:[1,0]
	v_pk_add_f32 v[16:17], v[16:17], 1.0 op_sel_hi:[1,0]
	v_max_f32_e32 v15, 0x4b000001, v15
	v_max_f32_e32 v14, 0x4b000001, v14
	v_pk_add_f32 v[12:13], v[12:13], 1.0 op_sel_hi:[1,0]
	v_pk_add_f32 v[10:11], v[10:11], 1.0 op_sel_hi:[1,0]
	v_pk_add_f32 v[8:9], v[8:9], 1.0 op_sel_hi:[1,0]
	v_rcp_f32_e32 v6, v6
	v_rcp_f32_e32 v7, v7
	v_pk_add_f32 v[4:5], v[4:5], 1.0 op_sel_hi:[1,0]
	v_rcp_f32_e32 v2, v2
	v_rcp_f32_e32 v3, v3
	v_rcp_f32_e32 v16, v16
	v_rcp_f32_e32 v17, v17
	v_perm_b32 v20, v15, v14, s58
	v_rcp_f32_e32 v14, v10
	v_rcp_f32_e32 v12, v12
	v_rcp_f32_e32 v13, v13
	v_rcp_f32_e32 v15, v11
	v_rcp_f32_e32 v8, v8
	v_rcp_f32_e32 v9, v9
	v_rcp_f32_e32 v4, v4
	v_rcp_f32_e32 v5, v5
	v_pk_fma_f32 v[6:7], v[6:7], s[26:27], v[126:127] op_sel_hi:[1,0,0]
	v_pk_fma_f32 v[2:3], v[2:3], s[26:27], v[126:127] op_sel_hi:[1,0,0]
	v_pk_fma_f32 v[16:17], v[16:17], s[26:27], v[126:127] op_sel_hi:[1,0,0]
	v_pk_fma_f32 v[12:13], v[12:13], s[26:27], v[126:127] op_sel_hi:[1,0,0]
	v_pk_fma_f32 v[14:15], v[14:15], s[26:27], v[126:127] op_sel_hi:[1,0,0]
	v_pk_fma_f32 v[8:9], v[8:9], s[26:27], v[126:127] op_sel_hi:[1,0,0]
	v_max_f32_e32 v7, 0x4b000001, v7
	v_max_f32_e32 v6, 0x4b000001, v6
	v_pk_fma_f32 v[4:5], v[4:5], s[26:27], v[126:127] op_sel_hi:[1,0,0]
	v_max_f32_e32 v3, 0x4b000001, v3
	v_max_f32_e32 v2, 0x4b000001, v2
	v_mad_i64_i32 v[18:19], s[2:3], v123, s57, v[142:143]
	v_max_f32_e32 v17, 0x4b000001, v17
	v_max_f32_e32 v16, 0x4b000001, v16
	v_max_f32_e32 v11, 0x4b000001, v15
	v_max_f32_e32 v14, 0x4b000001, v14
	v_max_f32_e32 v13, 0x4b000001, v13
	v_max_f32_e32 v12, 0x4b000001, v12
	v_perm_b32 v6, v7, v6, s58
	v_max_f32_e32 v7, 0x4b000001, v9
	v_max_f32_e32 v8, 0x4b000001, v8
	v_perm_b32 v2, v3, v2, s58
	v_max_f32_e32 v3, 0x4b000001, v5
	v_max_f32_e32 v4, 0x4b000001, v4
	v_lshl_add_u64 v[18:19], v[18:19], 0, s[0:1]
	v_perm_b32 v10, v17, v16, s58
	v_perm_b32 v11, v11, v14, s58
	v_perm_b32 v12, v13, v12, s58
	v_perm_b32 v7, v7, v8, s58
	v_perm_b32 v3, v3, v4, s58
	v_lshl_add_u64 v[18:19], v[18:19], 0, v[154:155]
	v_lshl_or_b32 v10, v10, 16, v20
	v_lshl_or_b32 v11, v12, 16, v11
	v_lshl_or_b32 v12, v7, 16, v6
	v_lshl_or_b32 v13, v3, 16, v2
	global_store_dwordx4 v[18:19], v[10:13], off
	s_andn2_b64 vcc, exec, s[4:5]
	s_mov_b64 s[0:1], -1
	s_cbranch_vccnz .LBB0_2544
	s_andn2_b64 vcc, exec, s[6:7]
	s_cbranch_vccnz .LBB0_2543
	s_barrier
	s_branch .LBB0_2543
